# attention epilogues: v_permlane32_swap half-wave exchange then dwordx4 stores (half as many store instructions, same bytes)
# speedup vs baseline: 1.0495x; 1.0015x over previous
; template <int DQK, int DV, bool BIAS> ...
;     ...
;     l += __shfl_xor(l, 32);
;     const float inv = 1.f / l;
; #pragma unroll
;     for (int d = 0; d < NDT; ++d)
; #pragma unroll
;         for (int r = 0; r < 16; ++r) o[d][r] *= inv;
; __device__ __forceinline__ void attn_phase(PPtr P, int li, LAS unsigned char* lds, int vcu, int wave, int lane) {
;     ...
;         attn_pass<64, 128, true>(lds, proj + qrow * LDP + C_AQ + h * 128 + 64, LDP, nullptr, 0, proj + seq0 * LDP + C_AK + h * 128 + 64, LDP, nullptr, 0, proj + seq0 * LDP + C_AV + h * 128, LDP, qb * 256 + wave * 32, 0.125f * LOG2E, slope * LOG2E, nullptr, o2);
;         const float s1 = wave_sum(P->in[7][li * 64 + lane] * P->in[8][li * 64 + lane]), s2 = wave_sum(P->in[9][li * 64 + lane] * P->in[10][li * 64 + lane]);
;         const float lam_init = 0.8f - 0.6f * expf(-0.3f * (float)li); const float lam = expf(s1) - expf(s2) + lam_init;
.LBB0_598:
	s_barrier
	s_load_dwordx8 s[4:11], s[20:21], 0x38
	v_lshlrev_b32_e32 v66, 2, v173
	s_waitcnt lgkmcnt(0)
	global_load_dword v82, v66, s[4:5]
	global_load_dword v83, v66, s[6:7]
	global_load_dword v84, v66, s[8:9]
	global_load_dword v85, v66, s[10:11]
	v_xor_b32_e32 v87, 1, v170
	v_cmp_lt_i32_e32 vcc, v87, v172
	s_load_dwordx2 s[4:5], s[20:21], 0x58
	ds_read2st64_b32 v[66:67], v171 offset1:1
	ds_read2st64_b32 v[68:69], v171 offset0:2 offset1:3
	ds_read2st64_b32 v[70:71], v171 offset0:4 offset1:5
	ds_read2st64_b32 v[72:73], v171 offset0:6 offset1:7
	ds_read2st64_b32 v[74:75], v171 offset0:8 offset1:9
	ds_read2st64_b32 v[76:77], v171 offset0:10 offset1:11
	ds_read2st64_b32 v[78:79], v171 offset0:12 offset1:13
	ds_read2st64_b32 v[80:81], v171 offset0:14 offset1:15
	v_cndmask_b32_e32 v87, v170, v87, vcc
	v_lshlrev_b32_e32 v87, 2, v87
	s_waitcnt vmcnt(6) lgkmcnt(0)
	v_lshlrev_b32_e32 v130, 16, v66
	v_and_b32_e32 v131, 0xffff0000, v66
	v_lshlrev_b32_e32 v132, 16, v67
	v_and_b32_e32 v133, 0xffff0000, v67
	v_xor_b32_e32 v88, 2, v170
	v_cmp_lt_i32_e32 vcc, v88, v172
	s_waitcnt vmcnt(5)
	v_lshlrev_b32_e32 v136, 16, v68
	v_and_b32_e32 v137, 0xffff0000, v68
	v_cndmask_b32_e32 v88, v170, v88, vcc
	v_lshlrev_b32_e32 v88, 2, v88
	s_waitcnt vmcnt(4)
	v_lshlrev_b32_e32 v138, 16, v69
	v_and_b32_e32 v139, 0xffff0000, v69
	v_xor_b32_e32 v89, 4, v170
	v_cmp_lt_i32_e32 vcc, v89, v172
	v_xor_b32_e32 v90, 8, v170
	v_xor_b32_e32 v91, 16, v170
	v_cndmask_b32_e32 v89, v170, v89, vcc
	v_lshlrev_b32_e32 v89, 2, v89
	v_cmp_lt_i32_e32 vcc, v90, v172
	ds_bpermute_b32 v86, v168, v151
	v_lshlrev_b32_e32 v140, 16, v70
	v_cndmask_b32_e32 v90, v170, v90, vcc
	v_lshlrev_b32_e32 v90, 2, v90
	v_cmp_lt_i32_e32 vcc, v91, v172
	s_waitcnt lgkmcnt(0)
	v_add_f32_e32 v86, v151, v86
	v_and_b32_e32 v141, 0xffff0000, v70
	v_cndmask_b32_e32 v91, v170, v91, vcc
	v_lshlrev_b32_e32 v91, 2, v91
	v_div_scale_f32 v70, s[6:7], v86, v86, 1.0
	v_lshlrev_b32_e32 v144, 16, v72
	v_and_b32_e32 v145, 0xffff0000, v72
	v_rcp_f32_e32 v72, v70
	v_lshlrev_b32_e32 v146, 16, v73
	v_and_b32_e32 v147, 0xffff0000, v73
	v_lshlrev_b32_e32 v142, 16, v71
	v_fma_f32 v73, -v70, v72, 1.0
	v_and_b32_e32 v143, 0xffff0000, v71
	v_div_scale_f32 v71, vcc, 1.0, v86, 1.0
	v_fmac_f32_e32 v72, v73, v72
	v_mul_f32_e32 v73, v71, v72
	v_lshlrev_b32_e32 v148, 16, v74
	v_and_b32_e32 v149, 0xffff0000, v74
	v_fma_f32 v74, -v70, v73, v71
	s_mov_b32 s8, 0x3fb8aa3b
	v_fmac_f32_e32 v73, v74, v72
	v_fma_f32 v70, -v70, v73, v71
	v_lshlrev_b32_e32 v152, 16, v75
	v_and_b32_e32 v153, 0xffff0000, v75
	v_lshlrev_b32_e32 v156, 16, v76
	v_and_b32_e32 v157, 0xffff0000, v76
	s_mov_b32 s9, 0xc2ce8ed0
	v_div_fmas_f32 v70, v70, v72, v73
	s_mov_b32 s10, 0x42b17218
	v_mov_b32_e32 v92, 0x7f800000
	v_div_fixup_f32 v150, v70, v86, 1.0
	v_lshlrev_b32_e32 v158, 16, v77
	v_and_b32_e32 v159, 0xffff0000, v77
	v_lshlrev_b32_e32 v162, 16, v78
	v_and_b32_e32 v163, 0xffff0000, v78
	v_lshlrev_b32_e32 v164, 16, v79
	v_and_b32_e32 v165, 0xffff0000, v79
	v_lshlrev_b32_e32 v166, 16, v80
	v_and_b32_e32 v167, 0xffff0000, v80
	v_lshlrev_b32_e32 v172, 16, v81
	v_and_b32_e32 v173, 0xffff0000, v81
	v_pk_mul_f32 v[4:5], v[4:5], v[150:151] op_sel_hi:[1,0]
	v_pk_mul_f32 v[2:3], v[2:3], v[150:151] op_sel_hi:[1,0]
	v_pk_mul_f32 v[6:7], v[6:7], v[150:151] op_sel_hi:[1,0]
	v_pk_mul_f32 v[8:9], v[8:9], v[150:151] op_sel_hi:[1,0]
	s_waitcnt vmcnt(2)
	v_mul_f32_e32 v66, v82, v83
	ds_bpermute_b32 v66, v87, v66
	s_waitcnt vmcnt(0)
	v_mul_f32_e32 v67, v84, v85
	ds_bpermute_b32 v67, v87, v67
	v_pk_mul_f32 v[10:11], v[10:11], v[150:151] op_sel_hi:[1,0]
	v_pk_mul_f32 v[12:13], v[12:13], v[150:151] op_sel_hi:[1,0]
	s_waitcnt lgkmcnt(1)
	v_fmac_f32_e32 v66, v82, v83
	ds_bpermute_b32 v68, v88, v66
	s_waitcnt lgkmcnt(1)
	v_fmac_f32_e32 v67, v84, v85
	ds_bpermute_b32 v69, v88, v67
	v_pk_mul_f32 v[14:15], v[14:15], v[150:151] op_sel_hi:[1,0]
	v_pk_mul_f32 v[16:17], v[16:17], v[150:151] op_sel_hi:[1,0]
	s_waitcnt lgkmcnt(1)
	v_add_f32_e32 v66, v66, v68
	ds_bpermute_b32 v68, v89, v66
	s_waitcnt lgkmcnt(1)
	v_add_f32_e32 v67, v67, v69
	ds_bpermute_b32 v69, v89, v67
	v_pk_mul_f32 v[18:19], v[18:19], v[150:151] op_sel_hi:[1,0]
	v_pk_mul_f32 v[20:21], v[20:21], v[150:151] op_sel_hi:[1,0]
	s_waitcnt lgkmcnt(1)
	v_add_f32_e32 v66, v66, v68
	ds_bpermute_b32 v68, v90, v66
	s_waitcnt lgkmcnt(1)
	v_add_f32_e32 v67, v67, v69
	ds_bpermute_b32 v69, v90, v67
	v_pk_mul_f32 v[22:23], v[22:23], v[150:151] op_sel_hi:[1,0]
	v_pk_mul_f32 v[24:25], v[24:25], v[150:151] op_sel_hi:[1,0]
	s_waitcnt lgkmcnt(1)
	v_add_f32_e32 v66, v66, v68
	ds_bpermute_b32 v68, v91, v66
	s_waitcnt lgkmcnt(1)
	v_add_f32_e32 v67, v67, v69
	ds_bpermute_b32 v69, v91, v67
	v_pk_mul_f32 v[26:27], v[26:27], v[150:151] op_sel_hi:[1,0]
	v_pk_mul_f32 v[28:29], v[28:29], v[150:151] op_sel_hi:[1,0]
	s_waitcnt lgkmcnt(1)
	v_add_f32_e32 v66, v66, v68
	ds_bpermute_b32 v68, v168, v66
	s_waitcnt lgkmcnt(1)
	v_add_f32_e32 v67, v67, v69
	ds_bpermute_b32 v69, v168, v67
	v_pk_mul_f32 v[30:31], v[30:31], v[150:151] op_sel_hi:[1,0]
	v_pk_mul_f32 v[32:33], v[32:33], v[150:151] op_sel_hi:[1,0]
	s_waitcnt lgkmcnt(1)
	v_add_f32_e32 v66, v66, v68
	v_mul_f32_e32 v68, 0x3fb8aa3b, v66
	s_waitcnt lgkmcnt(0)
; __device__ __forceinline__ void attn_phase(PPtr P, int li, LAS unsigned char* lds, int vcu, int wave, int lane) {
;     ...
;         const float s1 = wave_sum(P->in[7][li * 64 + lane] * P->in[8][li * 64 + lane]), s2 = wave_sum(P->in[9][li * 64 + lane] * P->in[10][li * 64 + lane]);
;         const float lam_init = 0.8f - 0.6f * expf(-0.3f * (float)li); const float lam = expf(s1) - expf(s2) + lam_init;
;         float ss = 0.f;
; #pragma unroll
;         for (int d = 0; d < 4; ++d)
; #pragma unroll
;             for (int r = 0; r < 8; ++r) { const unsigned w = o1s[(d * 8 + r) * 64]; const float v0 = bflo(w) - lam * o2[d][2 * r], v1 = bfhi(w) - lam * o2[d][2 * r + 1]; o1[d][2 * r] = v0; o1[d][2 * r + 1] = v1; ss += v0 * v0 + v1 * v1; }
	v_add_f32_e32 v67, v67, v69
	v_mul_f32_e32 v69, 0x3fb8aa3b, v67
	v_fma_f32 v71, v66, s8, -v68
	v_rndne_f32_e32 v74, v68
	v_fma_f32 v75, v67, s8, -v69
	v_rndne_f32_e32 v76, v69
	v_fmac_f32_e32 v71, 0x32a5705f, v66
	v_sub_f32_e32 v68, v68, v74
	v_fmac_f32_e32 v75, 0x32a5705f, v67
	v_sub_f32_e32 v69, v69, v76
	v_add_f32_e32 v68, v68, v71
	v_cvt_i32_f32_e32 v74, v74
	v_add_f32_e32 v69, v69, v75
	v_exp_f32_e32 v68, v68
	v_cvt_i32_f32_e32 v76, v76
	v_exp_f32_e32 v69, v69
	v_cmp_ngt_f32_e32 vcc, s9, v66
	v_ldexp_f32 v68, v68, v74
	v_pk_mul_f32 v[34:35], v[34:35], v[150:151] op_sel_hi:[1,0]
	v_ldexp_f32 v69, v69, v76
	v_cndmask_b32_e32 v68, 0, v68, vcc
	v_cmp_ngt_f32_e32 vcc, s9, v67
	v_pk_mul_f32 v[36:37], v[36:37], v[150:151] op_sel_hi:[1,0]
	v_pk_mul_f32 v[38:39], v[38:39], v[150:151] op_sel_hi:[1,0]
	v_cndmask_b32_e32 v69, 0, v69, vcc
	v_cmp_nlt_f32_e32 vcc, s10, v66
	v_pk_mul_f32 v[40:41], v[40:41], v[150:151] op_sel_hi:[1,0]
	v_pk_mul_f32 v[42:43], v[42:43], v[150:151] op_sel_hi:[1,0]
	v_cndmask_b32_e32 v66, v92, v68, vcc
	v_cmp_nlt_f32_e32 vcc, s10, v67
	v_pk_mul_f32 v[44:45], v[44:45], v[150:151] op_sel_hi:[1,0]
	v_pk_mul_f32 v[46:47], v[46:47], v[150:151] op_sel_hi:[1,0]
	v_cndmask_b32_e32 v67, v92, v69, vcc
	v_sub_f32_e32 v66, v66, v67
	v_add_f32_e32 v154, 0x3e4ccccc, v66
	ds_read2st64_b32 v[66:67], v171 offset0:16 offset1:17
	ds_read2st64_b32 v[68:69], v171 offset0:18 offset1:19
	ds_read2st64_b32 v[70:71], v171 offset0:20 offset1:21
	ds_read2st64_b32 v[72:73], v171 offset0:22 offset1:23
	v_pk_fma_f32 v[4:5], v[4:5], v[154:155], v[132:133] op_sel_hi:[1,0,1] neg_lo:[1,0,0] neg_hi:[1,0,0]
	v_pk_fma_f32 v[2:3], v[2:3], v[154:155], v[130:131] op_sel_hi:[1,0,1] neg_lo:[1,0,0] neg_hi:[1,0,0]
	s_waitcnt lgkmcnt(2)
	v_lshlrev_b32_e32 v178, 16, v68
	v_lshlrev_b32_e32 v174, 16, v66
	v_and_b32_e32 v175, 0xffff0000, v66
	v_lshlrev_b32_e32 v176, 16, v67
	v_and_b32_e32 v177, 0xffff0000, v67
	ds_read2st64_b32 v[66:67], v171 offset0:24 offset1:25
	v_and_b32_e32 v179, 0xffff0000, v68
	v_lshlrev_b32_e32 v180, 16, v69
	v_and_b32_e32 v181, 0xffff0000, v69
	s_waitcnt lgkmcnt(2)
	v_lshlrev_b32_e32 v182, 16, v70
	v_and_b32_e32 v183, 0xffff0000, v70
	v_lshlrev_b32_e32 v184, 16, v71
	v_and_b32_e32 v185, 0xffff0000, v71
	s_waitcnt lgkmcnt(1)
	v_lshlrev_b32_e32 v186, 16, v72
	v_and_b32_e32 v187, 0xffff0000, v72
	v_lshlrev_b32_e32 v188, 16, v73
	v_and_b32_e32 v189, 0xffff0000, v73
	ds_read2st64_b32 v[68:69], v171 offset0:26 offset1:27
	ds_read2st64_b32 v[70:71], v171 offset0:28 offset1:29
	ds_read2st64_b32 v[72:73], v171 offset0:30 offset1:31
	s_waitcnt lgkmcnt(3)
	v_lshlrev_b32_e32 v170, 16, v66
	v_and_b32_e32 v171, 0xffff0000, v66
	v_lshrrev_b32_e32 v66, 3, v169
	v_and_b32_e32 v134, 4, v66
	v_lshlrev_b32_e32 v66, 2, v134
	v_lshlrev_b32_e32 v190, 16, v67
	v_and_b32_e32 v191, 0xffff0000, v67
	s_waitcnt lgkmcnt(2)
	v_lshlrev_b32_e32 v192, 16, v68
	v_and_b32_e32 v193, 0xffff0000, v68
	v_lshlrev_b32_e32 v194, 16, v69
	v_and_b32_e32 v195, 0xffff0000, v69
	s_waitcnt lgkmcnt(1)
	v_lshlrev_b32_e32 v196, 16, v70
	v_and_b32_e32 v197, 0xffff0000, v70
	v_lshlrev_b32_e32 v198, 16, v71
	v_and_b32_e32 v199, 0xffff0000, v71
	s_waitcnt lgkmcnt(0)
	v_lshlrev_b32_e32 v160, 16, v72
	v_and_b32_e32 v161, 0xffff0000, v72
	v_lshlrev_b32_e32 v200, 16, v73
	v_and_b32_e32 v201, 0xffff0000, v73
	global_load_dwordx4 v[126:129], v66, s[4:5]
	global_load_dwordx4 v[122:125], v66, s[4:5] offset:32
	global_load_dwordx4 v[118:121], v66, s[4:5] offset:64
	global_load_dwordx4 v[114:117], v66, s[4:5] offset:96
	global_load_dwordx4 v[110:113], v66, s[4:5] offset:128
	global_load_dwordx4 v[106:109], v66, s[4:5] offset:160
	global_load_dwordx4 v[102:105], v66, s[4:5] offset:192
	global_load_dwordx4 v[98:101], v66, s[4:5] offset:224
	global_load_dwordx4 v[94:97], v66, s[4:5] offset:256
	global_load_dwordx4 v[90:93], v66, s[4:5] offset:288
	global_load_dwordx4 v[86:89], v66, s[4:5] offset:320
	global_load_dwordx4 v[82:85], v66, s[4:5] offset:352
	global_load_dwordx4 v[78:81], v66, s[4:5] offset:384
	global_load_dwordx4 v[74:77], v66, s[4:5] offset:416
	global_load_dwordx4 v[70:73], v66, s[4:5] offset:448
	s_nop 0
	global_load_dwordx4 v[66:69], v66, s[4:5] offset:480
	v_pk_fma_f32 v[6:7], v[6:7], v[154:155], v[136:137] op_sel_hi:[1,0,1] neg_lo:[1,0,0] neg_hi:[1,0,0]
	v_pk_mul_f32 v[132:133], v[4:5], v[4:5]
	v_pk_mul_f32 v[130:131], v[2:3], v[2:3]
	v_pk_fma_f32 v[8:9], v[8:9], v[154:155], v[138:139] op_sel_hi:[1,0,1] neg_lo:[1,0,0] neg_hi:[1,0,0]
	v_pk_mul_f32 v[136:137], v[6:7], v[6:7]
	v_add_f32_e32 v132, v132, v133
	v_add_f32_e32 v130, v130, v131
	v_pk_fma_f32 v[10:11], v[10:11], v[154:155], v[140:141] op_sel_hi:[1,0,1] neg_lo:[1,0,0] neg_hi:[1,0,0]
	v_pk_mul_f32 v[138:139], v[8:9], v[8:9]
	v_add_f32_e32 v130, v130, v132
	v_add_f32_e32 v131, v136, v137
	v_pk_fma_f32 v[12:13], v[12:13], v[154:155], v[142:143] op_sel_hi:[1,0,1] neg_lo:[1,0,0] neg_hi:[1,0,0]
	v_pk_mul_f32 v[140:141], v[10:11], v[10:11]
	v_add_f32_e32 v130, v131, v130
	v_add_f32_e32 v131, v138, v139
	v_pk_fma_f32 v[14:15], v[14:15], v[154:155], v[144:145] op_sel_hi:[1,0,1] neg_lo:[1,0,0] neg_hi:[1,0,0]
	v_pk_mul_f32 v[142:143], v[12:13], v[12:13]
	v_add_f32_e32 v130, v131, v130
	v_add_f32_e32 v131, v140, v141
	v_pk_fma_f32 v[16:17], v[16:17], v[154:155], v[146:147] op_sel_hi:[1,0,1] neg_lo:[1,0,0] neg_hi:[1,0,0]
	v_pk_mul_f32 v[144:145], v[14:15], v[14:15]
	v_add_f32_e32 v130, v131, v130
	v_add_f32_e32 v131, v142, v143
	v_pk_fma_f32 v[18:19], v[18:19], v[154:155], v[148:149] op_sel_hi:[1,0,1] neg_lo:[1,0,0] neg_hi:[1,0,0]
	v_pk_mul_f32 v[146:147], v[16:17], v[16:17]
	v_add_f32_e32 v130, v131, v130
	v_add_f32_e32 v131, v144, v145
; __device__ __forceinline__ void attn_phase(PPtr P, int li, LAS unsigned char* lds, int vcu, int wave, int lane) {
;     ...
;             for (int r = 0; r < 8; ++r) { const unsigned w = o1s[(d * 8 + r) * 64]; const float v0 = bflo(w) - lam * o2[d][2 * r], v1 = bfhi(w) - lam * o2[d][2 * r + 1]; o1[d][2 * r] = v0; o1[d][2 * r + 1] = v1; ss += v0 * v0 + v1 * v1; }
;         ss += __shfl_xor(ss, 32);
	v_pk_fma_f32 v[20:21], v[20:21], v[154:155], v[152:153] op_sel_hi:[1,0,1] neg_lo:[1,0,0] neg_hi:[1,0,0]
	v_pk_mul_f32 v[148:149], v[18:19], v[18:19]
	v_add_f32_e32 v130, v131, v130
	v_add_f32_e32 v131, v146, v147
	v_pk_fma_f32 v[22:23], v[22:23], v[154:155], v[156:157] op_sel_hi:[1,0,1] neg_lo:[1,0,0] neg_hi:[1,0,0]
	v_pk_mul_f32 v[152:153], v[20:21], v[20:21]
	v_add_f32_e32 v130, v131, v130
	v_add_f32_e32 v131, v148, v149
	v_pk_fma_f32 v[24:25], v[24:25], v[154:155], v[158:159] op_sel_hi:[1,0,1] neg_lo:[1,0,0] neg_hi:[1,0,0]
	v_pk_mul_f32 v[156:157], v[22:23], v[22:23]
	v_add_f32_e32 v130, v131, v130
	v_add_f32_e32 v131, v152, v153
	v_pk_fma_f32 v[26:27], v[26:27], v[154:155], v[162:163] op_sel_hi:[1,0,1] neg_lo:[1,0,0] neg_hi:[1,0,0]
	v_pk_mul_f32 v[158:159], v[24:25], v[24:25]
	v_add_f32_e32 v130, v131, v130
	v_add_f32_e32 v131, v156, v157
	v_pk_fma_f32 v[28:29], v[28:29], v[154:155], v[164:165] op_sel_hi:[1,0,1] neg_lo:[1,0,0] neg_hi:[1,0,0]
	v_pk_mul_f32 v[162:163], v[26:27], v[26:27]
	v_add_f32_e32 v130, v131, v130
	v_add_f32_e32 v131, v158, v159
	v_pk_fma_f32 v[30:31], v[30:31], v[154:155], v[166:167] op_sel_hi:[1,0,1] neg_lo:[1,0,0] neg_hi:[1,0,0]
	v_pk_mul_f32 v[164:165], v[28:29], v[28:29]
	v_add_f32_e32 v130, v131, v130
	v_add_f32_e32 v131, v162, v163
	v_pk_fma_f32 v[32:33], v[32:33], v[154:155], v[172:173] op_sel_hi:[1,0,1] neg_lo:[1,0,0] neg_hi:[1,0,0]
	v_pk_mul_f32 v[166:167], v[30:31], v[30:31]
	v_add_f32_e32 v130, v131, v130
	v_add_f32_e32 v131, v164, v165
	v_pk_fma_f32 v[34:35], v[34:35], v[154:155], v[174:175] op_sel_hi:[1,0,1] neg_lo:[1,0,0] neg_hi:[1,0,0]
	v_pk_mul_f32 v[172:173], v[32:33], v[32:33]
	v_add_f32_e32 v130, v131, v130
	v_add_f32_e32 v131, v166, v167
	v_pk_fma_f32 v[36:37], v[36:37], v[154:155], v[176:177] op_sel_hi:[1,0,1] neg_lo:[1,0,0] neg_hi:[1,0,0]
	v_pk_mul_f32 v[174:175], v[34:35], v[34:35]
	v_add_f32_e32 v130, v131, v130
	v_add_f32_e32 v131, v172, v173
	v_pk_fma_f32 v[38:39], v[38:39], v[154:155], v[178:179] op_sel_hi:[1,0,1] neg_lo:[1,0,0] neg_hi:[1,0,0]
	v_pk_mul_f32 v[176:177], v[36:37], v[36:37]
	v_add_f32_e32 v130, v131, v130
	v_add_f32_e32 v131, v174, v175
	v_pk_fma_f32 v[40:41], v[40:41], v[154:155], v[180:181] op_sel_hi:[1,0,1] neg_lo:[1,0,0] neg_hi:[1,0,0]
	v_pk_mul_f32 v[178:179], v[38:39], v[38:39]
	v_add_f32_e32 v130, v131, v130
	v_add_f32_e32 v131, v176, v177
	v_pk_fma_f32 v[42:43], v[42:43], v[154:155], v[182:183] op_sel_hi:[1,0,1] neg_lo:[1,0,0] neg_hi:[1,0,0]
	v_pk_mul_f32 v[180:181], v[40:41], v[40:41]
	v_add_f32_e32 v130, v131, v130
	v_add_f32_e32 v131, v178, v179
	v_pk_fma_f32 v[44:45], v[44:45], v[154:155], v[184:185] op_sel_hi:[1,0,1] neg_lo:[1,0,0] neg_hi:[1,0,0]
	v_pk_mul_f32 v[182:183], v[42:43], v[42:43]
	v_add_f32_e32 v130, v131, v130
	v_add_f32_e32 v131, v180, v181
	v_pk_mul_f32 v[48:49], v[48:49], v[150:151] op_sel_hi:[1,0]
	v_pk_fma_f32 v[46:47], v[46:47], v[154:155], v[186:187] op_sel_hi:[1,0,1] neg_lo:[1,0,0] neg_hi:[1,0,0]
	v_pk_mul_f32 v[184:185], v[44:45], v[44:45]
	v_add_f32_e32 v130, v131, v130
	v_add_f32_e32 v131, v182, v183
	v_pk_mul_f32 v[50:51], v[50:51], v[150:151] op_sel_hi:[1,0]
	v_pk_fma_f32 v[48:49], v[48:49], v[154:155], v[188:189] op_sel_hi:[1,0,1] neg_lo:[1,0,0] neg_hi:[1,0,0]
	v_pk_mul_f32 v[186:187], v[46:47], v[46:47]
	v_add_f32_e32 v130, v131, v130
	v_add_f32_e32 v131, v184, v185
	v_pk_mul_f32 v[56:57], v[56:57], v[150:151] op_sel_hi:[1,0]
	v_pk_mul_f32 v[54:55], v[54:55], v[150:151] op_sel_hi:[1,0]
	v_pk_mul_f32 v[52:53], v[52:53], v[150:151] op_sel_hi:[1,0]
	v_pk_fma_f32 v[50:51], v[50:51], v[154:155], v[170:171] op_sel_hi:[1,0,1] neg_lo:[1,0,0] neg_hi:[1,0,0]
	v_pk_mul_f32 v[188:189], v[48:49], v[48:49]
	v_add_f32_e32 v130, v131, v130
	v_add_f32_e32 v131, v186, v187
	v_pk_fma_f32 v[56:57], v[56:57], v[154:155], v[194:195] op_sel_hi:[1,0,1] neg_lo:[1,0,0] neg_hi:[1,0,0]
	v_pk_fma_f32 v[54:55], v[54:55], v[154:155], v[192:193] op_sel_hi:[1,0,1] neg_lo:[1,0,0] neg_hi:[1,0,0]
	v_pk_fma_f32 v[52:53], v[52:53], v[154:155], v[190:191] op_sel_hi:[1,0,1] neg_lo:[1,0,0] neg_hi:[1,0,0]
	v_pk_mul_f32 v[170:171], v[50:51], v[50:51]
	v_add_f32_e32 v130, v131, v130
	v_add_f32_e32 v131, v188, v189
	v_pk_mul_f32 v[60:61], v[60:61], v[150:151] op_sel_hi:[1,0]
	v_pk_mul_f32 v[58:59], v[58:59], v[150:151] op_sel_hi:[1,0]
	v_mov_b32_e32 v194, v57
	v_mov_b32_e32 v195, v55
	v_pk_mul_f32 v[190:191], v[52:53], v[52:53]
	v_add_f32_e32 v130, v131, v130
	v_add_f32_e32 v131, v170, v171
	v_pk_fma_f32 v[60:61], v[60:61], v[154:155], v[198:199] op_sel_hi:[1,0,1] neg_lo:[1,0,0] neg_hi:[1,0,0]
	v_pk_fma_f32 v[58:59], v[58:59], v[154:155], v[196:197] op_sel_hi:[1,0,1] neg_lo:[1,0,0] neg_hi:[1,0,0]
	v_mov_b32_e32 v192, v56
	v_mov_b32_e32 v193, v54
	v_pk_mul_f32 v[194:195], v[194:195], v[194:195]
	v_add_f32_e32 v130, v131, v130
	v_add_f32_e32 v131, v190, v191
	v_pk_mul_f32 v[64:65], v[64:65], v[150:151] op_sel_hi:[1,0]
	v_pk_mul_f32 v[62:63], v[62:63], v[150:151] op_sel_hi:[1,0]
	v_mov_b32_e32 v198, v61
	v_mov_b32_e32 v199, v59
	v_pk_fma_f32 v[192:193], v[192:193], v[192:193], v[194:195]
	v_add_f32_e32 v130, v131, v130
	v_pk_fma_f32 v[64:65], v[64:65], v[154:155], v[200:201] op_sel_hi:[1,0,1] neg_lo:[1,0,0] neg_hi:[1,0,0]
	v_pk_fma_f32 v[62:63], v[62:63], v[154:155], v[160:161] op_sel_hi:[1,0,1] neg_lo:[1,0,0] neg_hi:[1,0,0]
	v_mov_b32_e32 v196, v60
	v_mov_b32_e32 v197, v58
	v_pk_mul_f32 v[198:199], v[198:199], v[198:199]
	v_add_f32_e32 v130, v193, v130
	v_mov_b32_e32 v200, v65
	v_mov_b32_e32 v201, v63
	v_pk_fma_f32 v[196:197], v[196:197], v[196:197], v[198:199]
	v_add_f32_e32 v130, v192, v130
	v_mov_b32_e32 v160, v64
	v_mov_b32_e32 v161, v62
	v_pk_mul_f32 v[200:201], v[200:201], v[200:201]
	v_add_f32_e32 v130, v197, v130
	v_pk_fma_f32 v[160:161], v[160:161], v[160:161], v[200:201]
	v_add_f32_e32 v130, v196, v130
	v_add_f32_e32 v130, v161, v130
	v_add_f32_e32 v130, v160, v130
	ds_bpermute_b32 v131, v168, v130
	v_and_b32_e32 v138, 31, v169
	s_bfe_u32 s34, s33, 0x30004
	s_add_u32 s27, s46, s27
	s_addc_u32 s48, s47, 0
	s_waitcnt lgkmcnt(0)
; __device__ __forceinline__ unsigned cvtpk(float lo, float hi) { typedef __bf16 bf2 __attribute__((ext_vector_type(2))); f32x2 v = {lo, hi}; bf2 b = __builtin_convertvector(v, bf2); return __builtin_bit_cast(unsigned, b); }
; template <int NDT> __device__ __forceinline__ void attn_store(const f32x16 (&o)[NDT], bf16_t* Ow, int ldo, int r32, int hi) {
;     ...
;         for (int q = 0; q < 4; ++q) { u32x2 w; w.x = cvtpk(o[d][4 * q], o[d][4 * q + 1]); w.y = cvtpk(o[d][4 * q + 2], o[d][4 * q + 3]); *(u32x2*)(Ow + (size_t)r32 * ldo + 32 * d + 8 * q + 4 * hi) = w; }
; __device__ __forceinline__ void attn_phase(PPtr P, int li, LAS unsigned char* lds, int vcu, int wave, int lane) {
;     ...
;         const float rs = __builtin_amdgcn_rsqf(ss * (1.f / 128) + EPSN) * (1.f - lam_init);
;         const float* sub = P->in[11] + li * 128;
; #pragma unroll
;         for (int d = 0; d < 4; ++d)
; #pragma unroll
;             for (int q = 0; q < 4; ++q) { const f32x4 gg = *(const f32x4*)(sub + 32 * d + 8 * q + 4 * hi);
;                 o1[d][4 * q] *= rs * gg[0]; o1[d][4 * q + 1] *= rs * gg[1]; o1[d][4 * q + 2] *= rs * gg[2]; o1[d][4 * q + 3] *= rs * gg[3]; }
;         attn_store<4>(o1, proj + qrow * LDP + C_AQ + h * 128, LDP, r32, hi);
	v_add_f32_e32 v130, v130, v131
	v_mov_b32_e32 v131, 0x358637bd
	v_fmac_f32_e32 v131, 0x3c000000, v130
	v_rsq_f32_e32 v130, v131
	v_mov_b32_e32 v131, 0
	s_lshl_b32 s7, s34, 6
	s_and_b32 s6, s33, 64
	v_mul_f32_e32 v130, 0x3f4ccccd, v130
	s_waitcnt vmcnt(0)
	v_pk_mul_f32 v[66:67], v[130:131], v[66:67] op_sel_hi:[0,1]
	v_pk_mul_f32 v[62:63], v[62:63], v[66:67]
	v_pk_mul_f32 v[66:67], v[130:131], v[68:69] op_sel_hi:[0,1]
	v_pk_mul_f32 v[126:127], v[126:127], v[130:131] op_sel_hi:[1,0]
	v_pk_mul_f32 v[122:123], v[122:123], v[130:131] op_sel_hi:[1,0]
	v_pk_mul_f32 v[118:119], v[118:119], v[130:131] op_sel_hi:[1,0]
	v_pk_mul_f32 v[114:115], v[114:115], v[130:131] op_sel_hi:[1,0]
	v_pk_mul_f32 v[110:111], v[110:111], v[130:131] op_sel_hi:[1,0]
	v_pk_mul_f32 v[106:107], v[106:107], v[130:131] op_sel_hi:[1,0]
	v_pk_mul_f32 v[102:103], v[102:103], v[130:131] op_sel_hi:[1,0]
	v_pk_mul_f32 v[98:99], v[98:99], v[130:131] op_sel_hi:[1,0]
	v_pk_mul_f32 v[94:95], v[94:95], v[130:131] op_sel_hi:[1,0]
	v_pk_mul_f32 v[90:91], v[130:131], v[90:91] op_sel_hi:[0,1]
	v_pk_mul_f32 v[86:87], v[130:131], v[86:87] op_sel_hi:[0,1]
	v_pk_mul_f32 v[82:83], v[130:131], v[82:83] op_sel_hi:[0,1]
	v_pk_mul_f32 v[78:79], v[130:131], v[78:79] op_sel_hi:[0,1]
	v_pk_mul_f32 v[74:75], v[130:131], v[74:75] op_sel_hi:[0,1]
	v_pk_mul_f32 v[70:71], v[130:131], v[70:71] op_sel_hi:[0,1]
	v_pk_mul_f32 v[64:65], v[64:65], v[66:67]
	v_mul_u32_u24_e32 v66, 0xca0, v138
	v_pk_mul_f32 v[2:3], v[2:3], v[126:127]
	v_pk_mul_f32 v[126:127], v[128:129], v[130:131] op_sel_hi:[1,0]
	v_pk_mul_f32 v[6:7], v[6:7], v[122:123]
	v_pk_mul_f32 v[122:123], v[124:125], v[130:131] op_sel_hi:[1,0]
	v_pk_mul_f32 v[10:11], v[10:11], v[118:119]
	v_pk_mul_f32 v[118:119], v[120:121], v[130:131] op_sel_hi:[1,0]
	v_pk_mul_f32 v[14:15], v[14:15], v[114:115]
	v_pk_mul_f32 v[114:115], v[116:117], v[130:131] op_sel_hi:[1,0]
	v_pk_mul_f32 v[18:19], v[18:19], v[110:111]
	v_pk_mul_f32 v[110:111], v[112:113], v[130:131] op_sel_hi:[1,0]
	v_pk_mul_f32 v[22:23], v[22:23], v[106:107]
	v_pk_mul_f32 v[106:107], v[108:109], v[130:131] op_sel_hi:[1,0]
	v_pk_mul_f32 v[26:27], v[26:27], v[102:103]
	v_pk_mul_f32 v[102:103], v[104:105], v[130:131] op_sel_hi:[1,0]
	v_pk_mul_f32 v[30:31], v[30:31], v[98:99]
	v_pk_mul_f32 v[98:99], v[100:101], v[130:131] op_sel_hi:[1,0]
	v_pk_mul_f32 v[34:35], v[34:35], v[94:95]
	v_pk_mul_f32 v[94:95], v[96:97], v[130:131] op_sel_hi:[1,0]
	v_pk_mul_f32 v[38:39], v[38:39], v[90:91]
	v_pk_mul_f32 v[90:91], v[130:131], v[92:93] op_sel_hi:[0,1]
	v_pk_mul_f32 v[42:43], v[42:43], v[86:87]
	v_pk_mul_f32 v[86:87], v[130:131], v[88:89] op_sel_hi:[0,1]
	v_pk_mul_f32 v[46:47], v[46:47], v[82:83]
	v_pk_mul_f32 v[82:83], v[130:131], v[84:85] op_sel_hi:[0,1]
	v_pk_mul_f32 v[50:51], v[50:51], v[78:79]
	v_pk_mul_f32 v[78:79], v[130:131], v[80:81] op_sel_hi:[0,1]
	v_pk_mul_f32 v[54:55], v[54:55], v[74:75]
	v_pk_mul_f32 v[74:75], v[130:131], v[76:77] op_sel_hi:[0,1]
	v_pk_mul_f32 v[58:59], v[58:59], v[70:71]
	v_pk_mul_f32 v[70:71], v[130:131], v[72:73] op_sel_hi:[0,1]
	v_lshlrev_b32_e32 v130, 1, v66
	v_pk_mul_f32 v[4:5], v[4:5], v[126:127]
	v_lshl_add_u64 v[68:69], s[18:19], 0, v[130:131]
	v_lshlrev_b32_e32 v130, 1, v134
	v_pk_mul_f32 v[8:9], v[8:9], v[122:123]
	v_lshl_add_u64 v[68:69], v[68:69], 0, v[130:131]
	v_cvt_pk_bf16_f32 v232, v2, v3
	v_cvt_pk_bf16_f32 v233, v4, v5
	v_pk_mul_f32 v[12:13], v[12:13], v[118:119]
	v_cvt_pk_bf16_f32 v234, v6, v7
	v_cvt_pk_bf16_f32 v235, v8, v9
	v_pk_mul_f32 v[16:17], v[16:17], v[114:115]
	v_mbcnt_lo_u32_b32 v246, -1, 0
	v_mbcnt_hi_u32_b32 v246, -1, v246
	v_and_b32_e32 v246, 32, v246
	v_lshrrev_b32_e32 v246, 2, v246
	v_mov_b32_e32 v247, 0
	v_lshl_add_u64 v[244:245], v[68:69], 0, v[246:247]
	s_nop 1
	v_permlane32_swap_b32 v232, v234
	v_permlane32_swap_b32 v233, v235
	global_store_dwordx4 v[244:245], v[232:235], off
	v_cvt_pk_bf16_f32 v236, v10, v11
	v_cvt_pk_bf16_f32 v237, v12, v13
	v_pk_mul_f32 v[20:21], v[20:21], v[110:111]
	v_cvt_pk_bf16_f32 v238, v14, v15
	v_cvt_pk_bf16_f32 v239, v16, v17
	v_pk_mul_f32 v[24:25], v[24:25], v[106:107]
	s_nop 1
	v_permlane32_swap_b32 v236, v238
	v_permlane32_swap_b32 v237, v239
	global_store_dwordx4 v[244:245], v[236:239], off offset:32
	v_cvt_pk_bf16_f32 v240, v18, v19
	v_cvt_pk_bf16_f32 v241, v20, v21
	v_pk_mul_f32 v[28:29], v[28:29], v[102:103]
	v_cvt_pk_bf16_f32 v242, v22, v23
	v_cvt_pk_bf16_f32 v243, v24, v25
	v_pk_mul_f32 v[32:33], v[32:33], v[98:99]
	s_nop 1
	v_permlane32_swap_b32 v240, v242
	v_permlane32_swap_b32 v241, v243
	global_store_dwordx4 v[244:245], v[240:243], off offset:64
	v_cvt_pk_bf16_f32 v232, v26, v27
	v_cvt_pk_bf16_f32 v233, v28, v29
	v_pk_mul_f32 v[36:37], v[36:37], v[94:95]
	v_cvt_pk_bf16_f32 v234, v30, v31
	v_cvt_pk_bf16_f32 v235, v32, v33
	v_pk_mul_f32 v[40:41], v[40:41], v[90:91]
	s_nop 1
	v_permlane32_swap_b32 v232, v234
	v_permlane32_swap_b32 v233, v235
	global_store_dwordx4 v[244:245], v[232:235], off offset:96
	v_cvt_pk_bf16_f32 v236, v34, v35
	v_cvt_pk_bf16_f32 v237, v36, v37
	v_pk_mul_f32 v[44:45], v[44:45], v[86:87]
	v_cvt_pk_bf16_f32 v238, v38, v39
	v_cvt_pk_bf16_f32 v239, v40, v41
	v_pk_mul_f32 v[48:49], v[48:49], v[82:83]
	s_nop 1
	v_permlane32_swap_b32 v236, v238
	v_permlane32_swap_b32 v237, v239
	global_store_dwordx4 v[244:245], v[236:239], off offset:128
	v_cvt_pk_bf16_f32 v240, v42, v43
	v_cvt_pk_bf16_f32 v241, v44, v45
	s_lshl_b32 s4, s34, 7
	v_pk_mul_f32 v[52:53], v[52:53], v[78:79]
	v_cvt_pk_bf16_f32 v242, v46, v47
	v_cvt_pk_bf16_f32 v243, v48, v49
	s_add_u32 s35, s16, s4
	v_pk_mul_f32 v[56:57], v[56:57], v[74:75]
	s_nop 1
	v_permlane32_swap_b32 v240, v242
	v_permlane32_swap_b32 v241, v243
	global_store_dwordx4 v[244:245], v[240:243], off offset:160
	v_cvt_pk_bf16_f32 v232, v50, v51
	v_cvt_pk_bf16_f32 v233, v52, v53
	s_addc_u32 s36, s17, 0
	s_lshl_b32 s4, s33, 1
	v_pk_mul_f32 v[60:61], v[60:61], v[70:71]
	v_cvt_pk_bf16_f32 v234, v54, v55
	v_cvt_pk_bf16_f32 v235, v56, v57
	s_and_b32 s4, s4, 0x80
	s_nop 1
	v_permlane32_swap_b32 v232, v234
	v_permlane32_swap_b32 v233, v235
	global_store_dwordx4 v[244:245], v[232:235], off offset:192
	v_cvt_pk_bf16_f32 v236, v58, v59
	v_cvt_pk_bf16_f32 v237, v60, v61
	s_add_u32 s4, s16, s4
	s_mov_b32 s20, 0
	v_cvt_pk_bf16_f32 v238, v62, v63
	v_cvt_pk_bf16_f32 v239, v64, v65
	s_addc_u32 s5, s17, 0
	s_mov_b64 s[10:11], -1
	s_movk_i32 s37, 0x1940
	s_lshl_b32 s38, s6, 1
	s_mov_b32 s6, 0x3e38aa3b
	s_movk_i32 s39, 0x90
	s_movk_i32 s40, 0x1000
	s_mov_b32 s41, 0x65000
	s_mov_b32 s42, 0x66000
	s_mov_b32 s43, 0xca000
	s_mov_b32 s44, 0xcb000
	s_mov_b32 s45, 0x12f000
	s_mov_b32 s46, 0x130000
	s_mov_b32 s47, 0x41000000
	v_lshlrev_b32_e32 v132, 1, v66
	v_lshlrev_b32_e32 v146, 1, v134
	v_mov_b32_e32 v139, 0x1940000
	s_nop 1
	v_permlane32_swap_b32 v236, v238
	v_permlane32_swap_b32 v237, v239
	global_store_dwordx4 v[244:245], v[236:239], off offset:224
	s_branch .LBB0_600
; __device__ __forceinline__ unsigned cvtpk(float lo, float hi) { typedef __bf16 bf2 __attribute__((ext_vector_type(2))); f32x2 v = {lo, hi}; bf2 b = __builtin_convertvector(v, bf2); return __builtin_bit_cast(unsigned, b); }
; template <int DQK, int DV, bool BIAS> ...
;     ...
;     l += __shfl_xor(l, 32);
;     const float inv = 1.f / l;
; #pragma unroll
;     for (int d = 0; d < NDT; ++d)
; #pragma unroll
;         for (int r = 0; r < 16; ++r) o[d][r] *= inv;
; }
; template <int NDT> __device__ __forceinline__ void attn_store(const f32x16 (&o)[NDT], bf16_t* Ow, int ldo, int r32, int hi) {
; #pragma unroll
;     for (int d = 0; d < NDT; ++d)
; #pragma unroll
;         for (int q = 0; q < 4; ++q) { u32x2 w; w.x = cvtpk(o[d][4 * q], o[d][4 * q + 1]); w.y = cvtpk(o[d][4 * q + 2], o[d][4 * q + 3]); *(u32x2*)(Ow + (size_t)r32 * ldo + 32 * d + 8 * q + 4 * hi) = w; }
; __device__ __forceinline__ void attn_phase(PPtr P, int li, LAS unsigned char* lds, int vcu, int wave, int lane) {
;     ...
;         attn_store<2>(o, proj + qrow * LDP + C_BQ + qh * 64, LDP, r32, hi);
.LBB0_599:
	ds_bpermute_b32 v34, v168, v144
	v_mov_b32_e32 v133, v131
	v_mov_b32_e32 v147, v131
	s_waitcnt lgkmcnt(0)
	s_barrier
	v_add_f32_e32 v34, v144, v34
	v_div_scale_f32 v35, s[18:19], v34, v34, 1.0
	v_rcp_f32_e32 v36, v35
	v_div_scale_f32 v37, vcc, 1.0, v34, 1.0
	v_fma_f32 v38, -v35, v36, 1.0
	v_fmac_f32_e32 v36, v38, v36
	v_mul_f32_e32 v38, v37, v36
	v_fma_f32 v39, -v35, v38, v37
	v_fmac_f32_e32 v38, v39, v36
	v_fma_f32 v35, -v35, v38, v37
	v_div_fmas_f32 v35, v35, v36, v38
	v_div_fixup_f32 v34, v35, v34, 1.0
	v_pk_mul_f32 v[18:19], v[18:19], v[34:35] op_sel_hi:[1,0]
	v_pk_mul_f32 v[20:21], v[20:21], v[34:35] op_sel_hi:[1,0]
	v_pk_mul_f32 v[22:23], v[22:23], v[34:35] op_sel_hi:[1,0]
	v_pk_mul_f32 v[24:25], v[24:25], v[34:35] op_sel_hi:[1,0]
	v_pk_mul_f32 v[26:27], v[26:27], v[34:35] op_sel_hi:[1,0]
	v_pk_mul_f32 v[28:29], v[28:29], v[34:35] op_sel_hi:[1,0]
	v_pk_mul_f32 v[30:31], v[30:31], v[34:35] op_sel_hi:[1,0]
	v_pk_mul_f32 v[32:33], v[32:33], v[34:35] op_sel_hi:[1,0]
	v_pk_mul_f32 v[2:3], v[2:3], v[34:35] op_sel_hi:[1,0]
	v_pk_mul_f32 v[4:5], v[4:5], v[34:35] op_sel_hi:[1,0]
	v_pk_mul_f32 v[6:7], v[6:7], v[34:35] op_sel_hi:[1,0]
	v_pk_mul_f32 v[8:9], v[8:9], v[34:35] op_sel_hi:[1,0]
	v_pk_mul_f32 v[10:11], v[10:11], v[34:35] op_sel_hi:[1,0]
	v_pk_mul_f32 v[12:13], v[12:13], v[34:35] op_sel_hi:[1,0]
	v_pk_mul_f32 v[14:15], v[14:15], v[34:35] op_sel_hi:[1,0]
	v_pk_mul_f32 v[16:17], v[16:17], v[34:35] op_sel_hi:[1,0]
	v_lshl_add_u64 v[34:35], s[10:11], 0, v[132:133]
	v_lshl_add_u64 v[34:35], v[34:35], 0, v[146:147]
	v_cvt_pk_bf16_f32 v232, v18, v19
	v_cvt_pk_bf16_f32 v233, v20, v21
	v_cvt_pk_bf16_f32 v236, v2, v3
	v_cvt_pk_bf16_f32 v237, v4, v5
	v_cvt_pk_bf16_f32 v234, v22, v23
	v_cvt_pk_bf16_f32 v235, v24, v25
	v_cvt_pk_bf16_f32 v238, v6, v7
	v_cvt_pk_bf16_f32 v239, v8, v9
	v_mbcnt_lo_u32_b32 v246, -1, 0
	v_mbcnt_hi_u32_b32 v246, -1, v246
	v_and_b32_e32 v246, 32, v246
	v_lshrrev_b32_e32 v246, 2, v246
	v_mov_b32_e32 v247, 0
	v_lshl_add_u64 v[244:245], v[34:35], 0, v[246:247]
	s_nop 1
	v_permlane32_swap_b32 v232, v234
	v_permlane32_swap_b32 v233, v235
	global_store_dwordx4 v[244:245], v[232:235], off offset:3072
	v_cvt_pk_bf16_f32 v240, v26, v27
	v_cvt_pk_bf16_f32 v241, v28, v29
	s_nop 1
	v_permlane32_swap_b32 v236, v238
	v_permlane32_swap_b32 v237, v239
	global_store_dwordx4 v[244:245], v[236:239], off offset:3136
	v_cvt_pk_bf16_f32 v232, v10, v11
	v_cvt_pk_bf16_f32 v233, v12, v13
	v_cvt_pk_bf16_f32 v242, v30, v31
	v_cvt_pk_bf16_f32 v243, v32, v33
	v_cvt_pk_bf16_f32 v234, v14, v15
	v_cvt_pk_bf16_f32 v235, v16, v17
	s_movk_i32 s20, 0x100
	s_mov_b64 s[10:11], 0
	s_and_b64 vcc, exec, s[8:9]
	s_nop 1
	v_permlane32_swap_b32 v240, v242
	v_permlane32_swap_b32 v241, v243
	global_store_dwordx4 v[244:245], v[240:243], off offset:3104
	s_nop 1
	v_permlane32_swap_b32 v232, v234
	v_permlane32_swap_b32 v233, v235
	global_store_dwordx4 v[244:245], v[232:235], off offset:3168
	s_cbranch_vccnz .LBB0_616

; __device__ __forceinline__ unsigned cvtpk(float lo, float hi) { typedef __bf16 bf2 __attribute__((ext_vector_type(2))); f32x2 v = {lo, hi}; bf2 b = __builtin_convertvector(v, bf2); return __builtin_bit_cast(unsigned, b); }
; template <int DQK, int DV, bool BIAS> ...
;     ...
;     l += __shfl_xor(l, 32);
;     const float inv = 1.f / l;
; #pragma unroll
;     for (int d = 0; d < NDT; ++d)
; #pragma unroll
;         for (int r = 0; r < 16; ++r) o[d][r] *= inv;
; }
; template <int NDT> __device__ __forceinline__ void attn_store(const f32x16 (&o)[NDT], bf16_t* Ow, int ldo, int r32, int hi) {
; #pragma unroll
;     for (int d = 0; d < NDT; ++d)
; #pragma unroll
;         for (int q = 0; q < 4; ++q) { u32x2 w; w.x = cvtpk(o[d][4 * q], o[d][4 * q + 1]); w.y = cvtpk(o[d][4 * q + 2], o[d][4 * q + 3]); *(u32x2*)(Ow + (size_t)r32 * ldo + 32 * d + 8 * q + 4 * hi) = w; }
; __device__ __forceinline__ void attn_phase(PPtr P, int li, LAS unsigned char* lds, int vcu, int wave, int lane) {
;     ...
;         attn_store<2>(o, mlaq + qrow * 768 + h * 64, 768, r32, hi);
.LBB0_617:
	ds_bpermute_b32 v34, v168, v164
	v_mov_b32_e32 v151, v149
	v_mov_b32_e32 v147, v149
	s_waitcnt lgkmcnt(0)
	s_barrier
	v_add_f32_e32 v34, v164, v34
	v_div_scale_f32 v35, s[4:5], v34, v34, 1.0
	v_rcp_f32_e32 v36, v35
	v_div_scale_f32 v37, vcc, 1.0, v34, 1.0
	v_fma_f32 v38, -v35, v36, 1.0
	v_fmac_f32_e32 v36, v38, v36
	v_mul_f32_e32 v38, v37, v36
	v_fma_f32 v39, -v35, v38, v37
	v_fmac_f32_e32 v38, v39, v36
	v_fma_f32 v35, -v35, v38, v37
	v_div_fmas_f32 v35, v35, v36, v38
	v_div_fixup_f32 v34, v35, v34, 1.0
	v_pk_mul_f32 v[18:19], v[18:19], v[34:35] op_sel_hi:[1,0]
	v_pk_mul_f32 v[20:21], v[20:21], v[34:35] op_sel_hi:[1,0]
	v_pk_mul_f32 v[22:23], v[22:23], v[34:35] op_sel_hi:[1,0]
	v_pk_mul_f32 v[24:25], v[24:25], v[34:35] op_sel_hi:[1,0]
	v_pk_mul_f32 v[26:27], v[26:27], v[34:35] op_sel_hi:[1,0]
	v_pk_mul_f32 v[28:29], v[28:29], v[34:35] op_sel_hi:[1,0]
	v_pk_mul_f32 v[30:31], v[30:31], v[34:35] op_sel_hi:[1,0]
	v_pk_mul_f32 v[32:33], v[32:33], v[34:35] op_sel_hi:[1,0]
	v_pk_mul_f32 v[2:3], v[2:3], v[34:35] op_sel_hi:[1,0]
	v_pk_mul_f32 v[4:5], v[4:5], v[34:35] op_sel_hi:[1,0]
	v_pk_mul_f32 v[6:7], v[6:7], v[34:35] op_sel_hi:[1,0]
	v_pk_mul_f32 v[8:9], v[8:9], v[34:35] op_sel_hi:[1,0]
	v_pk_mul_f32 v[10:11], v[10:11], v[34:35] op_sel_hi:[1,0]
	v_pk_mul_f32 v[12:13], v[12:13], v[34:35] op_sel_hi:[1,0]
	v_pk_mul_f32 v[14:15], v[14:15], v[34:35] op_sel_hi:[1,0]
	v_pk_mul_f32 v[16:17], v[16:17], v[34:35] op_sel_hi:[1,0]
	v_lshl_add_u64 v[34:35], s[36:37], 0, v[150:151]
	v_lshl_add_u64 v[34:35], v[34:35], 0, v[146:147]
	v_cvt_pk_bf16_f32 v232, v18, v19
	v_cvt_pk_bf16_f32 v233, v20, v21
	v_cvt_pk_bf16_f32 v236, v2, v3
	v_cvt_pk_bf16_f32 v237, v4, v5
	v_cvt_pk_bf16_f32 v234, v22, v23
	v_cvt_pk_bf16_f32 v235, v24, v25
	v_cvt_pk_bf16_f32 v238, v6, v7
	v_cvt_pk_bf16_f32 v239, v8, v9
	v_mbcnt_lo_u32_b32 v246, -1, 0
	v_mbcnt_hi_u32_b32 v246, -1, v246
	v_and_b32_e32 v246, 32, v246
	v_lshrrev_b32_e32 v246, 2, v246
	v_mov_b32_e32 v247, 0
	v_lshl_add_u64 v[244:245], v[34:35], 0, v[246:247]
	s_nop 1
	v_permlane32_swap_b32 v232, v234
	v_permlane32_swap_b32 v233, v235
	global_store_dwordx4 v[244:245], v[232:235], off
	v_cvt_pk_bf16_f32 v240, v26, v27
	v_cvt_pk_bf16_f32 v241, v28, v29
	s_nop 1
	v_permlane32_swap_b32 v236, v238
	v_permlane32_swap_b32 v237, v239
	global_store_dwordx4 v[244:245], v[236:239], off offset:64
	v_cvt_pk_bf16_f32 v232, v10, v11
	v_cvt_pk_bf16_f32 v233, v12, v13
	v_cvt_pk_bf16_f32 v242, v30, v31
	v_cvt_pk_bf16_f32 v243, v32, v33
	v_cvt_pk_bf16_f32 v234, v14, v15
	v_cvt_pk_bf16_f32 v235, v16, v17
	s_movk_i32 s4, 0x100
	s_andn2_b64 vcc, exec, s[38:39]
	s_mov_b64 s[38:39], 0
	s_nop 1
	v_permlane32_swap_b32 v240, v242
	v_permlane32_swap_b32 v241, v243
	global_store_dwordx4 v[244:245], v[240:243], off offset:32
	s_nop 1
	v_permlane32_swap_b32 v232, v234
	v_permlane32_swap_b32 v233, v235
	global_store_dwordx4 v[244:245], v[232:235], off offset:96
	s_cbranch_vccz .LBB0_662

; template <int DQK, int DV, bool BIAS> ...
;     ...
;     l += __shfl_xor(l, 32);
;     const float inv = 1.f / l;
; #pragma unroll
;     for (int d = 0; d < NDT; ++d)
; #pragma unroll
;         for (int r = 0; r < 16; ++r) o[d][r] *= inv;
; __device__ __forceinline__ void attn_phase(PPtr P, int li, LAS unsigned char* lds, int vcu, int wave, int lane) {
;     ...
;         attn_pass<64, 128, true>(lds, proj + qrow * LDP + C_AQ + h * 128 + 64, LDP, nullptr, 0, proj + seq0 * LDP + C_AK + h * 128 + 64, LDP, nullptr, 0, proj + seq0 * LDP + C_AV + h * 128, LDP, qb * 256 + wave * 32, 0.125f * LOG2E, slope * LOG2E, nullptr, o2);
;         const float s1 = wave_sum(P->in[7][li * 64 + lane] * P->in[8][li * 64 + lane]), s2 = wave_sum(P->in[9][li * 64 + lane] * P->in[10][li * 64 + lane]);
;         const float lam_init = 0.8f - 0.6f * expf(-0.3f * (float)li); const float lam = expf(s1) - expf(s2) + lam_init;
.LBB0_2026:
	s_barrier
	s_load_dwordx8 s[4:11], s[20:21], 0x38
	v_lshlrev_b32_e32 v66, 2, v173
	s_waitcnt lgkmcnt(0)
	global_load_dword v82, v66, s[4:5] offset:256
	global_load_dword v83, v66, s[6:7] offset:256
	global_load_dword v84, v66, s[8:9] offset:256
	global_load_dword v85, v66, s[10:11] offset:256
	v_xor_b32_e32 v87, 1, v170
	v_cmp_lt_i32_e32 vcc, v87, v172
	s_load_dwordx2 s[4:5], s[20:21], 0x58
	ds_read2st64_b32 v[66:67], v171 offset1:1
	ds_read2st64_b32 v[68:69], v171 offset0:2 offset1:3
	ds_read2st64_b32 v[70:71], v171 offset0:4 offset1:5
	ds_read2st64_b32 v[72:73], v171 offset0:6 offset1:7
	ds_read2st64_b32 v[74:75], v171 offset0:8 offset1:9
	ds_read2st64_b32 v[76:77], v171 offset0:10 offset1:11
	ds_read2st64_b32 v[78:79], v171 offset0:12 offset1:13
	ds_read2st64_b32 v[80:81], v171 offset0:14 offset1:15
	v_cndmask_b32_e32 v87, v170, v87, vcc
	v_lshlrev_b32_e32 v87, 2, v87
	s_waitcnt vmcnt(6) lgkmcnt(0)
	v_lshlrev_b32_e32 v130, 16, v66
	v_and_b32_e32 v131, 0xffff0000, v66
	v_lshlrev_b32_e32 v132, 16, v67
	v_and_b32_e32 v133, 0xffff0000, v67
	v_xor_b32_e32 v88, 2, v170
	v_cmp_lt_i32_e32 vcc, v88, v172
	s_waitcnt vmcnt(5)
	v_lshlrev_b32_e32 v136, 16, v68
	v_and_b32_e32 v137, 0xffff0000, v68
	v_cndmask_b32_e32 v88, v170, v88, vcc
	v_lshlrev_b32_e32 v88, 2, v88
	s_waitcnt vmcnt(4)
	v_lshlrev_b32_e32 v138, 16, v69
	v_and_b32_e32 v139, 0xffff0000, v69
	v_xor_b32_e32 v89, 4, v170
	v_cmp_lt_i32_e32 vcc, v89, v172
	v_xor_b32_e32 v90, 8, v170
	v_xor_b32_e32 v91, 16, v170
	v_cndmask_b32_e32 v89, v170, v89, vcc
	v_lshlrev_b32_e32 v89, 2, v89
	v_cmp_lt_i32_e32 vcc, v90, v172
	ds_bpermute_b32 v86, v168, v151
	v_lshlrev_b32_e32 v140, 16, v70
	v_cndmask_b32_e32 v90, v170, v90, vcc
	v_lshlrev_b32_e32 v90, 2, v90
	v_cmp_lt_i32_e32 vcc, v91, v172
	s_waitcnt lgkmcnt(0)
	v_add_f32_e32 v86, v151, v86
	v_and_b32_e32 v141, 0xffff0000, v70
	v_cndmask_b32_e32 v91, v170, v91, vcc
	v_lshlrev_b32_e32 v91, 2, v91
	v_div_scale_f32 v70, s[6:7], v86, v86, 1.0
	v_lshlrev_b32_e32 v144, 16, v72
	v_and_b32_e32 v145, 0xffff0000, v72
	v_rcp_f32_e32 v72, v70
	v_lshlrev_b32_e32 v146, 16, v73
	v_and_b32_e32 v147, 0xffff0000, v73
	v_lshlrev_b32_e32 v142, 16, v71
	v_fma_f32 v73, -v70, v72, 1.0
	v_and_b32_e32 v143, 0xffff0000, v71
	v_div_scale_f32 v71, vcc, 1.0, v86, 1.0
	v_fmac_f32_e32 v72, v73, v72
	v_mul_f32_e32 v73, v71, v72
	v_lshlrev_b32_e32 v148, 16, v74
	v_and_b32_e32 v149, 0xffff0000, v74
	v_fma_f32 v74, -v70, v73, v71
	s_mov_b32 s8, 0x3fb8aa3b
	v_fmac_f32_e32 v73, v74, v72
	v_fma_f32 v70, -v70, v73, v71
	v_lshlrev_b32_e32 v152, 16, v75
	v_and_b32_e32 v153, 0xffff0000, v75
	v_lshlrev_b32_e32 v156, 16, v76
	v_and_b32_e32 v157, 0xffff0000, v76
	s_mov_b32 s9, 0xc2ce8ed0
	v_div_fmas_f32 v70, v70, v72, v73
	s_mov_b32 s10, 0x42b17218
	v_mov_b32_e32 v92, 0x7f800000
	v_div_fixup_f32 v150, v70, v86, 1.0
	v_lshlrev_b32_e32 v158, 16, v77
	v_and_b32_e32 v159, 0xffff0000, v77
	v_lshlrev_b32_e32 v162, 16, v78
	v_and_b32_e32 v163, 0xffff0000, v78
	v_lshlrev_b32_e32 v164, 16, v79
	v_and_b32_e32 v165, 0xffff0000, v79
	v_lshlrev_b32_e32 v166, 16, v80
	v_and_b32_e32 v167, 0xffff0000, v80
	v_lshlrev_b32_e32 v172, 16, v81
	v_and_b32_e32 v173, 0xffff0000, v81
	v_pk_mul_f32 v[4:5], v[4:5], v[150:151] op_sel_hi:[1,0]
	v_pk_mul_f32 v[2:3], v[2:3], v[150:151] op_sel_hi:[1,0]
	v_pk_mul_f32 v[6:7], v[6:7], v[150:151] op_sel_hi:[1,0]
	v_pk_mul_f32 v[8:9], v[8:9], v[150:151] op_sel_hi:[1,0]
	s_waitcnt vmcnt(2)
	v_mul_f32_e32 v66, v82, v83
	ds_bpermute_b32 v66, v87, v66
	s_waitcnt vmcnt(0)
	v_mul_f32_e32 v67, v84, v85
	ds_bpermute_b32 v67, v87, v67
	v_pk_mul_f32 v[10:11], v[10:11], v[150:151] op_sel_hi:[1,0]
	v_pk_mul_f32 v[12:13], v[12:13], v[150:151] op_sel_hi:[1,0]
	s_waitcnt lgkmcnt(1)
	v_fmac_f32_e32 v66, v82, v83
	ds_bpermute_b32 v68, v88, v66
	s_waitcnt lgkmcnt(1)
	v_fmac_f32_e32 v67, v84, v85
	ds_bpermute_b32 v69, v88, v67
	v_pk_mul_f32 v[14:15], v[14:15], v[150:151] op_sel_hi:[1,0]
	v_pk_mul_f32 v[16:17], v[16:17], v[150:151] op_sel_hi:[1,0]
	s_waitcnt lgkmcnt(1)
	v_add_f32_e32 v66, v66, v68
	ds_bpermute_b32 v68, v89, v66
	s_waitcnt lgkmcnt(1)
	v_add_f32_e32 v67, v67, v69
	ds_bpermute_b32 v69, v89, v67
	v_pk_mul_f32 v[18:19], v[18:19], v[150:151] op_sel_hi:[1,0]
	v_pk_mul_f32 v[20:21], v[20:21], v[150:151] op_sel_hi:[1,0]
	s_waitcnt lgkmcnt(1)
	v_add_f32_e32 v66, v66, v68
	ds_bpermute_b32 v68, v90, v66
	s_waitcnt lgkmcnt(1)
	v_add_f32_e32 v67, v67, v69
	ds_bpermute_b32 v69, v90, v67
	v_pk_mul_f32 v[22:23], v[22:23], v[150:151] op_sel_hi:[1,0]
	v_pk_mul_f32 v[24:25], v[24:25], v[150:151] op_sel_hi:[1,0]
	s_waitcnt lgkmcnt(1)
	v_add_f32_e32 v66, v66, v68
	ds_bpermute_b32 v68, v91, v66
	s_waitcnt lgkmcnt(1)
	v_add_f32_e32 v67, v67, v69
	ds_bpermute_b32 v69, v91, v67
	v_pk_mul_f32 v[26:27], v[26:27], v[150:151] op_sel_hi:[1,0]
	v_pk_mul_f32 v[28:29], v[28:29], v[150:151] op_sel_hi:[1,0]
	s_waitcnt lgkmcnt(1)
	v_add_f32_e32 v66, v66, v68
	ds_bpermute_b32 v68, v168, v66
	s_waitcnt lgkmcnt(1)
	v_add_f32_e32 v67, v67, v69
	ds_bpermute_b32 v69, v168, v67
	v_pk_mul_f32 v[30:31], v[30:31], v[150:151] op_sel_hi:[1,0]
	v_pk_mul_f32 v[32:33], v[32:33], v[150:151] op_sel_hi:[1,0]
	s_waitcnt lgkmcnt(1)
	v_add_f32_e32 v66, v66, v68
	v_mul_f32_e32 v68, 0x3fb8aa3b, v66
	s_waitcnt lgkmcnt(0)
; __device__ __forceinline__ void attn_phase(PPtr P, int li, LAS unsigned char* lds, int vcu, int wave, int lane) {
;     ...
;         const float s1 = wave_sum(P->in[7][li * 64 + lane] * P->in[8][li * 64 + lane]), s2 = wave_sum(P->in[9][li * 64 + lane] * P->in[10][li * 64 + lane]);
;         const float lam_init = 0.8f - 0.6f * expf(-0.3f * (float)li); const float lam = expf(s1) - expf(s2) + lam_init;
;         float ss = 0.f;
; #pragma unroll
;         for (int d = 0; d < 4; ++d)
; #pragma unroll
;             for (int r = 0; r < 8; ++r) { const unsigned w = o1s[(d * 8 + r) * 64]; const float v0 = bflo(w) - lam * o2[d][2 * r], v1 = bfhi(w) - lam * o2[d][2 * r + 1]; o1[d][2 * r] = v0; o1[d][2 * r + 1] = v1; ss += v0 * v0 + v1 * v1; }
	v_add_f32_e32 v67, v67, v69
	v_mul_f32_e32 v69, 0x3fb8aa3b, v67
	v_fma_f32 v71, v66, s8, -v68
	v_rndne_f32_e32 v74, v68
	v_fma_f32 v75, v67, s8, -v69
	v_rndne_f32_e32 v76, v69
	v_fmac_f32_e32 v71, 0x32a5705f, v66
	v_sub_f32_e32 v68, v68, v74
	v_fmac_f32_e32 v75, 0x32a5705f, v67
	v_sub_f32_e32 v69, v69, v76
	v_add_f32_e32 v68, v68, v71
	v_cvt_i32_f32_e32 v74, v74
	v_add_f32_e32 v69, v69, v75
	v_exp_f32_e32 v68, v68
	v_cvt_i32_f32_e32 v76, v76
	v_exp_f32_e32 v69, v69
	v_cmp_ngt_f32_e32 vcc, s9, v66
	v_ldexp_f32 v68, v68, v74
	v_pk_mul_f32 v[34:35], v[34:35], v[150:151] op_sel_hi:[1,0]
	v_ldexp_f32 v69, v69, v76
	v_cndmask_b32_e32 v68, 0, v68, vcc
	v_cmp_ngt_f32_e32 vcc, s9, v67
	v_pk_mul_f32 v[36:37], v[36:37], v[150:151] op_sel_hi:[1,0]
	v_pk_mul_f32 v[38:39], v[38:39], v[150:151] op_sel_hi:[1,0]
	v_cndmask_b32_e32 v69, 0, v69, vcc
	v_cmp_nlt_f32_e32 vcc, s10, v66
	v_pk_mul_f32 v[40:41], v[40:41], v[150:151] op_sel_hi:[1,0]
	v_pk_mul_f32 v[42:43], v[42:43], v[150:151] op_sel_hi:[1,0]
	v_cndmask_b32_e32 v66, v92, v68, vcc
	v_cmp_nlt_f32_e32 vcc, s10, v67
	v_pk_mul_f32 v[44:45], v[44:45], v[150:151] op_sel_hi:[1,0]
	v_pk_mul_f32 v[46:47], v[46:47], v[150:151] op_sel_hi:[1,0]
	v_cndmask_b32_e32 v67, v92, v69, vcc
	v_sub_f32_e32 v66, v66, v67
	v_add_f32_e32 v154, 0x3eb60549, v66
	ds_read2st64_b32 v[66:67], v171 offset0:16 offset1:17
	ds_read2st64_b32 v[68:69], v171 offset0:18 offset1:19
	ds_read2st64_b32 v[70:71], v171 offset0:20 offset1:21
	ds_read2st64_b32 v[72:73], v171 offset0:22 offset1:23
	v_pk_fma_f32 v[4:5], v[4:5], v[154:155], v[132:133] op_sel_hi:[1,0,1] neg_lo:[1,0,0] neg_hi:[1,0,0]
	v_pk_fma_f32 v[2:3], v[2:3], v[154:155], v[130:131] op_sel_hi:[1,0,1] neg_lo:[1,0,0] neg_hi:[1,0,0]
	s_waitcnt lgkmcnt(2)
	v_lshlrev_b32_e32 v178, 16, v68
	v_lshlrev_b32_e32 v174, 16, v66
	v_and_b32_e32 v175, 0xffff0000, v66
	v_lshlrev_b32_e32 v176, 16, v67
	v_and_b32_e32 v177, 0xffff0000, v67
	ds_read2st64_b32 v[66:67], v171 offset0:24 offset1:25
	v_and_b32_e32 v179, 0xffff0000, v68
	v_lshlrev_b32_e32 v180, 16, v69
	v_and_b32_e32 v181, 0xffff0000, v69
	s_waitcnt lgkmcnt(2)
	v_lshlrev_b32_e32 v182, 16, v70
	v_and_b32_e32 v183, 0xffff0000, v70
	v_lshlrev_b32_e32 v184, 16, v71
	v_and_b32_e32 v185, 0xffff0000, v71
	s_waitcnt lgkmcnt(1)
	v_lshlrev_b32_e32 v186, 16, v72
	v_and_b32_e32 v187, 0xffff0000, v72
	v_lshlrev_b32_e32 v188, 16, v73
	v_and_b32_e32 v189, 0xffff0000, v73
	ds_read2st64_b32 v[68:69], v171 offset0:26 offset1:27
	ds_read2st64_b32 v[70:71], v171 offset0:28 offset1:29
	ds_read2st64_b32 v[72:73], v171 offset0:30 offset1:31
	s_waitcnt lgkmcnt(3)
	v_lshlrev_b32_e32 v170, 16, v66
	v_and_b32_e32 v171, 0xffff0000, v66
	v_lshrrev_b32_e32 v66, 3, v169
	v_and_b32_e32 v134, 4, v66
	v_lshlrev_b32_e32 v66, 2, v134
	v_lshlrev_b32_e32 v190, 16, v67
	v_and_b32_e32 v191, 0xffff0000, v67
	s_waitcnt lgkmcnt(2)
	v_lshlrev_b32_e32 v192, 16, v68
	v_and_b32_e32 v193, 0xffff0000, v68
	v_lshlrev_b32_e32 v194, 16, v69
	v_and_b32_e32 v195, 0xffff0000, v69
	s_waitcnt lgkmcnt(1)
	v_lshlrev_b32_e32 v196, 16, v70
	v_and_b32_e32 v197, 0xffff0000, v70
	v_lshlrev_b32_e32 v198, 16, v71
	v_and_b32_e32 v199, 0xffff0000, v71
	s_waitcnt lgkmcnt(0)
	v_lshlrev_b32_e32 v160, 16, v72
	v_and_b32_e32 v161, 0xffff0000, v72
	v_lshlrev_b32_e32 v200, 16, v73
	v_and_b32_e32 v201, 0xffff0000, v73
	global_load_dwordx4 v[126:129], v66, s[4:5] offset:512
	global_load_dwordx4 v[122:125], v66, s[4:5] offset:544
	global_load_dwordx4 v[118:121], v66, s[4:5] offset:576
	global_load_dwordx4 v[114:117], v66, s[4:5] offset:608
	global_load_dwordx4 v[110:113], v66, s[4:5] offset:640
	global_load_dwordx4 v[106:109], v66, s[4:5] offset:672
	global_load_dwordx4 v[102:105], v66, s[4:5] offset:704
	global_load_dwordx4 v[98:101], v66, s[4:5] offset:736
	global_load_dwordx4 v[94:97], v66, s[4:5] offset:768
	global_load_dwordx4 v[90:93], v66, s[4:5] offset:800
	global_load_dwordx4 v[86:89], v66, s[4:5] offset:832
	global_load_dwordx4 v[82:85], v66, s[4:5] offset:864
	global_load_dwordx4 v[78:81], v66, s[4:5] offset:896
	global_load_dwordx4 v[74:77], v66, s[4:5] offset:928
	global_load_dwordx4 v[70:73], v66, s[4:5] offset:960
	s_nop 0
	global_load_dwordx4 v[66:69], v66, s[4:5] offset:992
	v_pk_fma_f32 v[6:7], v[6:7], v[154:155], v[136:137] op_sel_hi:[1,0,1] neg_lo:[1,0,0] neg_hi:[1,0,0]
	v_pk_mul_f32 v[132:133], v[4:5], v[4:5]
	v_pk_mul_f32 v[130:131], v[2:3], v[2:3]
	v_pk_fma_f32 v[8:9], v[8:9], v[154:155], v[138:139] op_sel_hi:[1,0,1] neg_lo:[1,0,0] neg_hi:[1,0,0]
	v_pk_mul_f32 v[136:137], v[6:7], v[6:7]
	v_add_f32_e32 v132, v132, v133
	v_add_f32_e32 v130, v130, v131
	v_pk_fma_f32 v[10:11], v[10:11], v[154:155], v[140:141] op_sel_hi:[1,0,1] neg_lo:[1,0,0] neg_hi:[1,0,0]
	v_pk_mul_f32 v[138:139], v[8:9], v[8:9]
	v_add_f32_e32 v130, v130, v132
	v_add_f32_e32 v131, v136, v137
	v_pk_fma_f32 v[12:13], v[12:13], v[154:155], v[142:143] op_sel_hi:[1,0,1] neg_lo:[1,0,0] neg_hi:[1,0,0]
	v_pk_mul_f32 v[140:141], v[10:11], v[10:11]
	v_add_f32_e32 v130, v131, v130
	v_add_f32_e32 v131, v138, v139
	v_pk_fma_f32 v[14:15], v[14:15], v[154:155], v[144:145] op_sel_hi:[1,0,1] neg_lo:[1,0,0] neg_hi:[1,0,0]
	v_pk_mul_f32 v[142:143], v[12:13], v[12:13]
	v_add_f32_e32 v130, v131, v130
	v_add_f32_e32 v131, v140, v141
	v_pk_fma_f32 v[16:17], v[16:17], v[154:155], v[146:147] op_sel_hi:[1,0,1] neg_lo:[1,0,0] neg_hi:[1,0,0]
	v_pk_mul_f32 v[144:145], v[14:15], v[14:15]
	v_add_f32_e32 v130, v131, v130
	v_add_f32_e32 v131, v142, v143
	v_pk_fma_f32 v[18:19], v[18:19], v[154:155], v[148:149] op_sel_hi:[1,0,1] neg_lo:[1,0,0] neg_hi:[1,0,0]
	v_pk_mul_f32 v[146:147], v[16:17], v[16:17]
	v_add_f32_e32 v130, v131, v130
	v_add_f32_e32 v131, v144, v145
; __device__ __forceinline__ void attn_phase(PPtr P, int li, LAS unsigned char* lds, int vcu, int wave, int lane) {
;     ...
;             for (int r = 0; r < 8; ++r) { const unsigned w = o1s[(d * 8 + r) * 64]; const float v0 = bflo(w) - lam * o2[d][2 * r], v1 = bfhi(w) - lam * o2[d][2 * r + 1]; o1[d][2 * r] = v0; o1[d][2 * r + 1] = v1; ss += v0 * v0 + v1 * v1; }
;         ss += __shfl_xor(ss, 32);
	v_pk_fma_f32 v[20:21], v[20:21], v[154:155], v[152:153] op_sel_hi:[1,0,1] neg_lo:[1,0,0] neg_hi:[1,0,0]
	v_pk_mul_f32 v[148:149], v[18:19], v[18:19]
	v_add_f32_e32 v130, v131, v130
	v_add_f32_e32 v131, v146, v147
	v_pk_fma_f32 v[22:23], v[22:23], v[154:155], v[156:157] op_sel_hi:[1,0,1] neg_lo:[1,0,0] neg_hi:[1,0,0]
	v_pk_mul_f32 v[152:153], v[20:21], v[20:21]
	v_add_f32_e32 v130, v131, v130
	v_add_f32_e32 v131, v148, v149
	v_pk_fma_f32 v[24:25], v[24:25], v[154:155], v[158:159] op_sel_hi:[1,0,1] neg_lo:[1,0,0] neg_hi:[1,0,0]
	v_pk_mul_f32 v[156:157], v[22:23], v[22:23]
	v_add_f32_e32 v130, v131, v130
	v_add_f32_e32 v131, v152, v153
	v_pk_fma_f32 v[26:27], v[26:27], v[154:155], v[162:163] op_sel_hi:[1,0,1] neg_lo:[1,0,0] neg_hi:[1,0,0]
	v_pk_mul_f32 v[158:159], v[24:25], v[24:25]
	v_add_f32_e32 v130, v131, v130
	v_add_f32_e32 v131, v156, v157
	v_pk_fma_f32 v[28:29], v[28:29], v[154:155], v[164:165] op_sel_hi:[1,0,1] neg_lo:[1,0,0] neg_hi:[1,0,0]
	v_pk_mul_f32 v[162:163], v[26:27], v[26:27]
	v_add_f32_e32 v130, v131, v130
	v_add_f32_e32 v131, v158, v159
	v_pk_fma_f32 v[30:31], v[30:31], v[154:155], v[166:167] op_sel_hi:[1,0,1] neg_lo:[1,0,0] neg_hi:[1,0,0]
	v_pk_mul_f32 v[164:165], v[28:29], v[28:29]
	v_add_f32_e32 v130, v131, v130
	v_add_f32_e32 v131, v162, v163
	v_pk_fma_f32 v[32:33], v[32:33], v[154:155], v[172:173] op_sel_hi:[1,0,1] neg_lo:[1,0,0] neg_hi:[1,0,0]
	v_pk_mul_f32 v[166:167], v[30:31], v[30:31]
	v_add_f32_e32 v130, v131, v130
	v_add_f32_e32 v131, v164, v165
	v_pk_fma_f32 v[34:35], v[34:35], v[154:155], v[174:175] op_sel_hi:[1,0,1] neg_lo:[1,0,0] neg_hi:[1,0,0]
	v_pk_mul_f32 v[172:173], v[32:33], v[32:33]
	v_add_f32_e32 v130, v131, v130
	v_add_f32_e32 v131, v166, v167
	v_pk_fma_f32 v[36:37], v[36:37], v[154:155], v[176:177] op_sel_hi:[1,0,1] neg_lo:[1,0,0] neg_hi:[1,0,0]
	v_pk_mul_f32 v[174:175], v[34:35], v[34:35]
	v_add_f32_e32 v130, v131, v130
	v_add_f32_e32 v131, v172, v173
	v_pk_fma_f32 v[38:39], v[38:39], v[154:155], v[178:179] op_sel_hi:[1,0,1] neg_lo:[1,0,0] neg_hi:[1,0,0]
	v_pk_mul_f32 v[176:177], v[36:37], v[36:37]
	v_add_f32_e32 v130, v131, v130
	v_add_f32_e32 v131, v174, v175
	v_pk_fma_f32 v[40:41], v[40:41], v[154:155], v[180:181] op_sel_hi:[1,0,1] neg_lo:[1,0,0] neg_hi:[1,0,0]
	v_pk_mul_f32 v[178:179], v[38:39], v[38:39]
	v_add_f32_e32 v130, v131, v130
	v_add_f32_e32 v131, v176, v177
	v_pk_fma_f32 v[42:43], v[42:43], v[154:155], v[182:183] op_sel_hi:[1,0,1] neg_lo:[1,0,0] neg_hi:[1,0,0]
	v_pk_mul_f32 v[180:181], v[40:41], v[40:41]
	v_add_f32_e32 v130, v131, v130
	v_add_f32_e32 v131, v178, v179
	v_pk_fma_f32 v[44:45], v[44:45], v[154:155], v[184:185] op_sel_hi:[1,0,1] neg_lo:[1,0,0] neg_hi:[1,0,0]
	v_pk_mul_f32 v[182:183], v[42:43], v[42:43]
	v_add_f32_e32 v130, v131, v130
	v_add_f32_e32 v131, v180, v181
	v_pk_mul_f32 v[48:49], v[48:49], v[150:151] op_sel_hi:[1,0]
	v_pk_fma_f32 v[46:47], v[46:47], v[154:155], v[186:187] op_sel_hi:[1,0,1] neg_lo:[1,0,0] neg_hi:[1,0,0]
	v_pk_mul_f32 v[184:185], v[44:45], v[44:45]
	v_add_f32_e32 v130, v131, v130
	v_add_f32_e32 v131, v182, v183
	v_pk_mul_f32 v[50:51], v[50:51], v[150:151] op_sel_hi:[1,0]
	v_pk_fma_f32 v[48:49], v[48:49], v[154:155], v[188:189] op_sel_hi:[1,0,1] neg_lo:[1,0,0] neg_hi:[1,0,0]
	v_pk_mul_f32 v[186:187], v[46:47], v[46:47]
	v_add_f32_e32 v130, v131, v130
	v_add_f32_e32 v131, v184, v185
	v_pk_mul_f32 v[56:57], v[56:57], v[150:151] op_sel_hi:[1,0]
	v_pk_mul_f32 v[54:55], v[54:55], v[150:151] op_sel_hi:[1,0]
	v_pk_mul_f32 v[52:53], v[52:53], v[150:151] op_sel_hi:[1,0]
	v_pk_fma_f32 v[50:51], v[50:51], v[154:155], v[170:171] op_sel_hi:[1,0,1] neg_lo:[1,0,0] neg_hi:[1,0,0]
	v_pk_mul_f32 v[188:189], v[48:49], v[48:49]
	v_add_f32_e32 v130, v131, v130
	v_add_f32_e32 v131, v186, v187
	v_pk_fma_f32 v[56:57], v[56:57], v[154:155], v[194:195] op_sel_hi:[1,0,1] neg_lo:[1,0,0] neg_hi:[1,0,0]
	v_pk_fma_f32 v[54:55], v[54:55], v[154:155], v[192:193] op_sel_hi:[1,0,1] neg_lo:[1,0,0] neg_hi:[1,0,0]
	v_pk_fma_f32 v[52:53], v[52:53], v[154:155], v[190:191] op_sel_hi:[1,0,1] neg_lo:[1,0,0] neg_hi:[1,0,0]
	v_pk_mul_f32 v[170:171], v[50:51], v[50:51]
	v_add_f32_e32 v130, v131, v130
	v_add_f32_e32 v131, v188, v189
	v_pk_mul_f32 v[60:61], v[60:61], v[150:151] op_sel_hi:[1,0]
	v_pk_mul_f32 v[58:59], v[58:59], v[150:151] op_sel_hi:[1,0]
	v_mov_b32_e32 v194, v57
	v_mov_b32_e32 v195, v55
	v_pk_mul_f32 v[190:191], v[52:53], v[52:53]
	v_add_f32_e32 v130, v131, v130
	v_add_f32_e32 v131, v170, v171
	v_pk_fma_f32 v[60:61], v[60:61], v[154:155], v[198:199] op_sel_hi:[1,0,1] neg_lo:[1,0,0] neg_hi:[1,0,0]
	v_pk_fma_f32 v[58:59], v[58:59], v[154:155], v[196:197] op_sel_hi:[1,0,1] neg_lo:[1,0,0] neg_hi:[1,0,0]
	v_mov_b32_e32 v192, v56
	v_mov_b32_e32 v193, v54
	v_pk_mul_f32 v[194:195], v[194:195], v[194:195]
	v_add_f32_e32 v130, v131, v130
	v_add_f32_e32 v131, v190, v191
	v_pk_mul_f32 v[64:65], v[64:65], v[150:151] op_sel_hi:[1,0]
	v_pk_mul_f32 v[62:63], v[62:63], v[150:151] op_sel_hi:[1,0]
	v_mov_b32_e32 v198, v61
	v_mov_b32_e32 v199, v59
	v_pk_fma_f32 v[192:193], v[192:193], v[192:193], v[194:195]
	v_add_f32_e32 v130, v131, v130
	v_pk_fma_f32 v[64:65], v[64:65], v[154:155], v[200:201] op_sel_hi:[1,0,1] neg_lo:[1,0,0] neg_hi:[1,0,0]
	v_pk_fma_f32 v[62:63], v[62:63], v[154:155], v[160:161] op_sel_hi:[1,0,1] neg_lo:[1,0,0] neg_hi:[1,0,0]
	v_mov_b32_e32 v196, v60
	v_mov_b32_e32 v197, v58
	v_pk_mul_f32 v[198:199], v[198:199], v[198:199]
	v_add_f32_e32 v130, v193, v130
	v_mov_b32_e32 v200, v65
	v_mov_b32_e32 v201, v63
	v_pk_fma_f32 v[196:197], v[196:197], v[196:197], v[198:199]
	v_add_f32_e32 v130, v192, v130
	v_mov_b32_e32 v160, v64
	v_mov_b32_e32 v161, v62
	v_pk_mul_f32 v[200:201], v[200:201], v[200:201]
	v_add_f32_e32 v130, v197, v130
	v_pk_fma_f32 v[160:161], v[160:161], v[160:161], v[200:201]
	v_add_f32_e32 v130, v196, v130
	v_add_f32_e32 v130, v161, v130
	v_add_f32_e32 v130, v160, v130
	ds_bpermute_b32 v131, v168, v130
	v_and_b32_e32 v138, 31, v169
	s_bfe_u32 s34, s33, 0x30004
	s_add_u32 s27, s46, s27
	s_addc_u32 s48, s47, 0
	s_waitcnt lgkmcnt(0)
; __device__ __forceinline__ unsigned cvtpk(float lo, float hi) { typedef __bf16 bf2 __attribute__((ext_vector_type(2))); f32x2 v = {lo, hi}; bf2 b = __builtin_convertvector(v, bf2); return __builtin_bit_cast(unsigned, b); }
; template <int NDT> __device__ __forceinline__ void attn_store(const f32x16 (&o)[NDT], bf16_t* Ow, int ldo, int r32, int hi) {
;     ...
;         for (int q = 0; q < 4; ++q) { u32x2 w; w.x = cvtpk(o[d][4 * q], o[d][4 * q + 1]); w.y = cvtpk(o[d][4 * q + 2], o[d][4 * q + 3]); *(u32x2*)(Ow + (size_t)r32 * ldo + 32 * d + 8 * q + 4 * hi) = w; }
; __device__ __forceinline__ void attn_phase(PPtr P, int li, LAS unsigned char* lds, int vcu, int wave, int lane) {
;     ...
;         const float rs = __builtin_amdgcn_rsqf(ss * (1.f / 128) + EPSN) * (1.f - lam_init);
;         const float* sub = P->in[11] + li * 128;
; #pragma unroll
;         for (int d = 0; d < 4; ++d)
; #pragma unroll
;             for (int q = 0; q < 4; ++q) { const f32x4 gg = *(const f32x4*)(sub + 32 * d + 8 * q + 4 * hi);
;                 o1[d][4 * q] *= rs * gg[0]; o1[d][4 * q + 1] *= rs * gg[1]; o1[d][4 * q + 2] *= rs * gg[2]; o1[d][4 * q + 3] *= rs * gg[3]; }
;         attn_store<4>(o1, proj + qrow * LDP + C_AQ + h * 128, LDP, r32, hi);
	v_add_f32_e32 v130, v130, v131
	v_mov_b32_e32 v131, 0x358637bd
	v_fmac_f32_e32 v131, 0x3c000000, v130
	v_rsq_f32_e32 v130, v131
	v_mov_b32_e32 v131, 0
	s_lshl_b32 s7, s34, 6
	s_and_b32 s6, s33, 64
	v_mul_f32_e32 v130, 0x3f24fd5c, v130
	s_waitcnt vmcnt(0)
	v_pk_mul_f32 v[66:67], v[130:131], v[66:67] op_sel_hi:[0,1]
	v_pk_mul_f32 v[62:63], v[62:63], v[66:67]
	v_pk_mul_f32 v[66:67], v[130:131], v[68:69] op_sel_hi:[0,1]
	v_pk_mul_f32 v[126:127], v[126:127], v[130:131] op_sel_hi:[1,0]
	v_pk_mul_f32 v[122:123], v[122:123], v[130:131] op_sel_hi:[1,0]
	v_pk_mul_f32 v[118:119], v[118:119], v[130:131] op_sel_hi:[1,0]
	v_pk_mul_f32 v[114:115], v[114:115], v[130:131] op_sel_hi:[1,0]
	v_pk_mul_f32 v[110:111], v[110:111], v[130:131] op_sel_hi:[1,0]
	v_pk_mul_f32 v[106:107], v[106:107], v[130:131] op_sel_hi:[1,0]
	v_pk_mul_f32 v[102:103], v[102:103], v[130:131] op_sel_hi:[1,0]
	v_pk_mul_f32 v[98:99], v[98:99], v[130:131] op_sel_hi:[1,0]
	v_pk_mul_f32 v[94:95], v[94:95], v[130:131] op_sel_hi:[1,0]
	v_pk_mul_f32 v[90:91], v[130:131], v[90:91] op_sel_hi:[0,1]
	v_pk_mul_f32 v[86:87], v[130:131], v[86:87] op_sel_hi:[0,1]
	v_pk_mul_f32 v[82:83], v[130:131], v[82:83] op_sel_hi:[0,1]
	v_pk_mul_f32 v[78:79], v[130:131], v[78:79] op_sel_hi:[0,1]
	v_pk_mul_f32 v[74:75], v[130:131], v[74:75] op_sel_hi:[0,1]
	v_pk_mul_f32 v[70:71], v[130:131], v[70:71] op_sel_hi:[0,1]
	v_pk_mul_f32 v[64:65], v[64:65], v[66:67]
	v_mul_u32_u24_e32 v66, 0xca0, v138
	v_pk_mul_f32 v[2:3], v[2:3], v[126:127]
	v_pk_mul_f32 v[126:127], v[128:129], v[130:131] op_sel_hi:[1,0]
	v_pk_mul_f32 v[6:7], v[6:7], v[122:123]
	v_pk_mul_f32 v[122:123], v[124:125], v[130:131] op_sel_hi:[1,0]
	v_pk_mul_f32 v[10:11], v[10:11], v[118:119]
	v_pk_mul_f32 v[118:119], v[120:121], v[130:131] op_sel_hi:[1,0]
	v_pk_mul_f32 v[14:15], v[14:15], v[114:115]
	v_pk_mul_f32 v[114:115], v[116:117], v[130:131] op_sel_hi:[1,0]
	v_pk_mul_f32 v[18:19], v[18:19], v[110:111]
	v_pk_mul_f32 v[110:111], v[112:113], v[130:131] op_sel_hi:[1,0]
	v_pk_mul_f32 v[22:23], v[22:23], v[106:107]
	v_pk_mul_f32 v[106:107], v[108:109], v[130:131] op_sel_hi:[1,0]
	v_pk_mul_f32 v[26:27], v[26:27], v[102:103]
	v_pk_mul_f32 v[102:103], v[104:105], v[130:131] op_sel_hi:[1,0]
	v_pk_mul_f32 v[30:31], v[30:31], v[98:99]
	v_pk_mul_f32 v[98:99], v[100:101], v[130:131] op_sel_hi:[1,0]
	v_pk_mul_f32 v[34:35], v[34:35], v[94:95]
	v_pk_mul_f32 v[94:95], v[96:97], v[130:131] op_sel_hi:[1,0]
	v_pk_mul_f32 v[38:39], v[38:39], v[90:91]
	v_pk_mul_f32 v[90:91], v[130:131], v[92:93] op_sel_hi:[0,1]
	v_pk_mul_f32 v[42:43], v[42:43], v[86:87]
	v_pk_mul_f32 v[86:87], v[130:131], v[88:89] op_sel_hi:[0,1]
	v_pk_mul_f32 v[46:47], v[46:47], v[82:83]
	v_pk_mul_f32 v[82:83], v[130:131], v[84:85] op_sel_hi:[0,1]
	v_pk_mul_f32 v[50:51], v[50:51], v[78:79]
	v_pk_mul_f32 v[78:79], v[130:131], v[80:81] op_sel_hi:[0,1]
	v_pk_mul_f32 v[54:55], v[54:55], v[74:75]
	v_pk_mul_f32 v[74:75], v[130:131], v[76:77] op_sel_hi:[0,1]
	v_pk_mul_f32 v[58:59], v[58:59], v[70:71]
	v_pk_mul_f32 v[70:71], v[130:131], v[72:73] op_sel_hi:[0,1]
	v_lshlrev_b32_e32 v130, 1, v66
	v_pk_mul_f32 v[4:5], v[4:5], v[126:127]
	v_lshl_add_u64 v[68:69], s[18:19], 0, v[130:131]
	v_lshlrev_b32_e32 v130, 1, v134
	v_pk_mul_f32 v[8:9], v[8:9], v[122:123]
	v_lshl_add_u64 v[68:69], v[68:69], 0, v[130:131]
	v_cvt_pk_bf16_f32 v232, v2, v3
	v_cvt_pk_bf16_f32 v233, v4, v5
	v_pk_mul_f32 v[12:13], v[12:13], v[118:119]
	v_cvt_pk_bf16_f32 v234, v6, v7
	v_cvt_pk_bf16_f32 v235, v8, v9
	v_pk_mul_f32 v[16:17], v[16:17], v[114:115]
	v_mbcnt_lo_u32_b32 v246, -1, 0
	v_mbcnt_hi_u32_b32 v246, -1, v246
	v_and_b32_e32 v246, 32, v246
	v_lshrrev_b32_e32 v246, 2, v246
	v_mov_b32_e32 v247, 0
	v_lshl_add_u64 v[244:245], v[68:69], 0, v[246:247]
	s_nop 1
	v_permlane32_swap_b32 v232, v234
	v_permlane32_swap_b32 v233, v235
	global_store_dwordx4 v[244:245], v[232:235], off
	v_cvt_pk_bf16_f32 v236, v10, v11
	v_cvt_pk_bf16_f32 v237, v12, v13
	v_pk_mul_f32 v[20:21], v[20:21], v[110:111]
	v_cvt_pk_bf16_f32 v238, v14, v15
	v_cvt_pk_bf16_f32 v239, v16, v17
	v_pk_mul_f32 v[24:25], v[24:25], v[106:107]
	s_nop 1
	v_permlane32_swap_b32 v236, v238
	v_permlane32_swap_b32 v237, v239
	global_store_dwordx4 v[244:245], v[236:239], off offset:32
	v_cvt_pk_bf16_f32 v240, v18, v19
	v_cvt_pk_bf16_f32 v241, v20, v21
	v_pk_mul_f32 v[28:29], v[28:29], v[102:103]
	v_cvt_pk_bf16_f32 v242, v22, v23
	v_cvt_pk_bf16_f32 v243, v24, v25
	v_pk_mul_f32 v[32:33], v[32:33], v[98:99]
	s_nop 1
	v_permlane32_swap_b32 v240, v242
	v_permlane32_swap_b32 v241, v243
	global_store_dwordx4 v[244:245], v[240:243], off offset:64
	v_cvt_pk_bf16_f32 v232, v26, v27
	v_cvt_pk_bf16_f32 v233, v28, v29
	v_pk_mul_f32 v[36:37], v[36:37], v[94:95]
	v_cvt_pk_bf16_f32 v234, v30, v31
	v_cvt_pk_bf16_f32 v235, v32, v33
	v_pk_mul_f32 v[40:41], v[40:41], v[90:91]
	s_nop 1
	v_permlane32_swap_b32 v232, v234
	v_permlane32_swap_b32 v233, v235
	global_store_dwordx4 v[244:245], v[232:235], off offset:96
	v_cvt_pk_bf16_f32 v236, v34, v35
	v_cvt_pk_bf16_f32 v237, v36, v37
	v_pk_mul_f32 v[44:45], v[44:45], v[86:87]
	v_cvt_pk_bf16_f32 v238, v38, v39
	v_cvt_pk_bf16_f32 v239, v40, v41
	v_pk_mul_f32 v[48:49], v[48:49], v[82:83]
	s_nop 1
	v_permlane32_swap_b32 v236, v238
	v_permlane32_swap_b32 v237, v239
	global_store_dwordx4 v[244:245], v[236:239], off offset:128
	v_cvt_pk_bf16_f32 v240, v42, v43
	v_cvt_pk_bf16_f32 v241, v44, v45
	s_lshl_b32 s4, s34, 7
	v_pk_mul_f32 v[52:53], v[52:53], v[78:79]
	v_cvt_pk_bf16_f32 v242, v46, v47
	v_cvt_pk_bf16_f32 v243, v48, v49
	s_add_u32 s35, s16, s4
	v_pk_mul_f32 v[56:57], v[56:57], v[74:75]
	s_nop 1
	v_permlane32_swap_b32 v240, v242
	v_permlane32_swap_b32 v241, v243
	global_store_dwordx4 v[244:245], v[240:243], off offset:160
	v_cvt_pk_bf16_f32 v232, v50, v51
	v_cvt_pk_bf16_f32 v233, v52, v53
	s_addc_u32 s36, s17, 0
	s_lshl_b32 s4, s33, 1
	v_pk_mul_f32 v[60:61], v[60:61], v[70:71]
	v_cvt_pk_bf16_f32 v234, v54, v55
	v_cvt_pk_bf16_f32 v235, v56, v57
	s_and_b32 s4, s4, 0x80
	s_nop 1
	v_permlane32_swap_b32 v232, v234
	v_permlane32_swap_b32 v233, v235
	global_store_dwordx4 v[244:245], v[232:235], off offset:192
	v_cvt_pk_bf16_f32 v236, v58, v59
	v_cvt_pk_bf16_f32 v237, v60, v61
	s_add_u32 s4, s16, s4
	s_mov_b32 s20, 0
	v_cvt_pk_bf16_f32 v238, v62, v63
	v_cvt_pk_bf16_f32 v239, v64, v65
	s_addc_u32 s5, s17, 0
	s_mov_b64 s[10:11], -1
	s_movk_i32 s37, 0x1940
	s_lshl_b32 s38, s6, 1
	s_mov_b32 s6, 0x3e38aa3b
	s_movk_i32 s39, 0x90
	s_movk_i32 s40, 0x1000
	s_mov_b32 s41, 0x65000
	s_mov_b32 s42, 0x66000
	s_mov_b32 s43, 0xca000
	s_mov_b32 s44, 0xcb000
	s_mov_b32 s45, 0x12f000
	s_mov_b32 s46, 0x130000
	s_mov_b32 s47, 0x41000000
	v_lshlrev_b32_e32 v132, 1, v66
	v_lshlrev_b32_e32 v146, 1, v134
	v_mov_b32_e32 v139, 0x1940000
	s_nop 1
	v_permlane32_swap_b32 v236, v238
	v_permlane32_swap_b32 v237, v239
	global_store_dwordx4 v[244:245], v[236:239], off offset:224
	s_branch .LBB0_2028
